# replace IEEE f32 division sequences in silu (x/(1+exp(-x))) by x*v_rcp_f32(1+exp(-x)) in SWIGLU epilogue, GDN conv (phase C) and GDN readout; f32 throughout
# speedup vs baseline: 1.0275x; 1.0220x over previous
.LBB0_510:
	s_or_b64 exec, exec, s[0:1]
	v_mul_f32_e32 v1, 0xbfb8aa3b, v2
	v_exp_f32_e32 v1, v1
	s_ashr_i32 s11, s10, 31
	s_ashr_i32 s9, s8, 31
	v_mov_b64_e32 v[12:13], s[10:11]
	v_add_f32_e32 v1, 1.0, v1
	s_mov_b32 s0, 0x8800
	v_mov_b32_e32 v49, v193
	v_rcp_f32_e32 v2, v1
	s_nop 0
	v_mov_b32_e32 v1, v2
	v_lshlrev_b32_e32 v2, 2, v52
	ds_write2st64_b32 v2, v1, v0 offset0:238 offset1:240
	v_mov_b64_e32 v[2:3], s[10:11]
	v_mad_i64_i32 v[2:3], s[0:1], v29, s0, v[2:3]
	v_or_b32_e32 v1, v2, v48
	v_mad_u64_u32 v[4:5], s[0:1], v1, 24, s[46:47]
	v_mad_i32_i24 v5, v3, 24, v5
	v_lshl_add_u64 v[2:3], s[8:9], 2, v[4:5]
	global_store_dword v[2:3], v0, off
.LBB0_511:
	s_or_b64 exec, exec, s[2:3]
	s_lshl_b64 s[0:1], s[12:13], 2
	v_lshlrev_b32_e32 v0, 1, v154
	s_add_u32 s0, s31, s0
	s_addc_u32 s1, s34, s1
	v_lshlrev_b32_e32 v0, 2, v0
	v_mov_b32_e32 v1, v177
	v_lshl_add_u64 v[2:3], s[0:1], 0, v[0:1]
	v_add_co_u32_e32 v4, vcc, s85, v2
	global_load_dwordx2 v[14:15], v0, s[0:1]
	s_nop 0
	v_addc_co_u32_e32 v5, vcc, 0, v3, vcc
	s_movk_i32 s0, 0x2000
	v_add_co_u32_e32 v10, vcc, s0, v2
	s_movk_i32 s0, 0x3000
	s_nop 0
	v_addc_co_u32_e32 v11, vcc, 0, v3, vcc
	v_add_co_u32_e32 v6, vcc, s0, v2
	s_movk_i32 s0, 0x4000
	s_nop 0
	v_addc_co_u32_e32 v7, vcc, 0, v3, vcc
	v_add_co_u32_e32 v8, vcc, s0, v2
	s_waitcnt vmcnt(1)
	v_lshlrev_b32_e32 v82, 16, v26
	v_addc_co_u32_e32 v9, vcc, 0, v3, vcc
	global_load_dwordx2 v[18:19], v[4:5], off offset:512
	global_load_dwordx2 v[16:17], v[6:7], off offset:1536
	global_load_dwordx2 v[20:21], v[8:9], off offset:2048
	global_load_dwordx2 v[22:23], v[10:11], off offset:1024
	v_and_b32_e32 v83, 0xffff0000, v26
	v_lshlrev_b32_e32 v46, 16, v25
	v_and_b32_e32 v47, 0xffff0000, v25
	v_lshlrev_b32_e32 v44, 16, v30
	v_and_b32_e32 v45, 0xffff0000, v30
	v_lshlrev_b32_e32 v42, 16, v27
	v_and_b32_e32 v43, 0xffff0000, v27
	v_and_b32_e32 v76, 3, v52
	v_lshlrev_b32_e32 v40, 16, v32
	v_and_b32_e32 v41, 0xffff0000, v32
	v_mul_lo_u32 v67, v51, s35
	v_mul_lo_u32 v1, v24, s35
	v_lshlrev_b32_e32 v36, 16, v34
	v_and_b32_e32 v37, 0xffff0000, v34
	v_lshlrev_b32_e32 v24, 16, v33
	v_and_b32_e32 v25, 0xffff0000, v33
	v_lshlrev_b32_e32 v26, 16, v50
	v_and_b32_e32 v27, 0xffff0000, v50
	v_lshlrev_b32_e32 v32, 16, v35
	v_and_b32_e32 v33, 0xffff0000, v35
	v_lshlrev_b32_e32 v34, 16, v66
	v_and_b32_e32 v35, 0xffff0000, v66
	v_or_b32_e32 v50, 7, v51
	v_lshlrev_b32_e32 v66, 6, v76
	v_lshlrev_b32_e32 v38, 16, v31
	v_and_b32_e32 v39, 0xffff0000, v31
	v_lshlrev_b32_e32 v30, 16, v53
	v_and_b32_e32 v31, 0xffff0000, v53
	v_add_u32_e32 v53, v0, v1
	v_mul_lo_u32 v1, v50, s35
	v_add_u32_e32 v66, v67, v66
	s_waitcnt vmcnt(4)
	v_pk_fma_f32 v[82:83], v[14:15], v[82:83], 0 op_sel_hi:[1,1,0]
	v_pk_fma_f32 v[84:85], v[14:15], v[46:47], 0 op_sel_hi:[1,1,0]
	s_waitcnt vmcnt(3)
	v_pk_fma_f32 v[46:47], v[18:19], v[46:47], v[82:83]
	v_pk_fma_f32 v[82:83], v[18:19], v[44:45], v[84:85]
	s_waitcnt vmcnt(0)
	v_pk_fma_f32 v[46:47], v[22:23], v[44:45], v[46:47]
	s_nop 0
	v_pk_fma_f32 v[46:47], v[16:17], v[42:43], v[46:47]
	v_pk_fma_f32 v[82:83], v[22:23], v[42:43], v[82:83]
	v_pk_fma_f32 v[46:47], v[20:21], v[40:41], v[46:47]
	v_pk_fma_f32 v[82:83], v[16:17], v[40:41], v[82:83]
	v_mul_f32_e32 v50, 0xbfb8aa3b, v46
	v_mul_f32_e32 v67, 0xbfb8aa3b, v47
	v_exp_f32_e32 v86, v50
	v_exp_f32_e32 v87, v67
	v_pk_fma_f32 v[84:85], v[20:21], v[38:39], v[82:83]
	v_pk_fma_f32 v[44:45], v[14:15], v[44:45], 0 op_sel_hi:[1,1,0]
	v_mul_f32_e32 v77, 0xbfb8aa3b, v84
	v_pk_add_f32 v[86:87], v[86:87], 1.0 op_sel_hi:[1,0]
	v_mul_f32_e32 v82, 0xbfb8aa3b, v85
	v_exp_f32_e32 v88, v77
	v_exp_f32_e32 v89, v82
	s_nop 0
	v_pk_add_f32 v[88:89], v[88:89], 1.0 op_sel_hi:[1,0]
	v_rcp_f32_e32 v50, v87
	s_nop 0
	v_mul_f32_e32 v47, v47, v50
	v_rcp_f32_e32 v77, v86
	s_nop 0
	v_mul_f32_e32 v46, v46, v77
	v_pk_fma_f32 v[44:45], v[18:19], v[42:43], v[44:45]
	v_pk_fma_f32 v[44:45], v[22:23], v[40:41], v[44:45]
	v_pk_fma_f32 v[44:45], v[16:17], v[38:39], v[44:45]
	v_pk_fma_f32 v[44:45], v[20:21], v[36:37], v[44:45]
	v_mul_f32_e32 v86, 0xbfb8aa3b, v44
	v_mul_f32_e32 v87, 0xbfb8aa3b, v45
	v_exp_f32_e32 v86, v86
	v_exp_f32_e32 v87, v87
	v_rcp_f32_e32 v50, v89
	s_nop 0
	v_mul_f32_e32 v50, v85, v50
	v_pk_add_f32 v[86:87], v[86:87], 1.0 op_sel_hi:[1,0]
	v_rcp_f32_e32 v77, v88
	s_nop 0
	v_mul_f32_e32 v77, v84, v77
	ds_write2_b32 v53, v77, v50 offset0:65 offset1:66
	v_pk_fma_f32 v[42:43], v[14:15], v[42:43], 0 op_sel_hi:[1,1,0]
	v_pk_fma_f32 v[42:43], v[18:19], v[40:41], v[42:43]
	v_pk_fma_f32 v[42:43], v[22:23], v[38:39], v[42:43]
	v_pk_fma_f32 v[42:43], v[16:17], v[36:37], v[42:43]
	v_rcp_f32_e32 v50, v87
	s_nop 0
	v_mul_f32_e32 v45, v45, v50
	v_pk_fma_f32 v[42:43], v[20:21], v[24:25], v[42:43]
	v_mul_f32_e32 v84, 0xbfb8aa3b, v42
	v_mul_f32_e32 v85, 0xbfb8aa3b, v43
	v_exp_f32_e32 v84, v84
	v_exp_f32_e32 v85, v85
	s_nop 0
	v_pk_add_f32 v[84:85], v[84:85], 1.0 op_sel_hi:[1,0]
	v_rcp_f32_e32 v50, v86
	s_nop 0
	v_mul_f32_e32 v44, v44, v50
	ds_write2_b64 v53, v[46:47], v[44:45] offset1:65
	v_pk_fma_f32 v[40:41], v[14:15], v[40:41], 0 op_sel_hi:[1,1,0]
	v_pk_fma_f32 v[40:41], v[18:19], v[38:39], v[40:41]
	v_pk_fma_f32 v[40:41], v[22:23], v[36:37], v[40:41]
	v_rcp_f32_e32 v44, v85
	s_nop 0
	v_mul_f32_e32 v43, v43, v44
	v_pk_fma_f32 v[40:41], v[16:17], v[24:25], v[40:41]
	v_pk_fma_f32 v[40:41], v[20:21], v[26:27], v[40:41]
	v_mul_f32_e32 v44, 0xbfb8aa3b, v40
	v_mul_f32_e32 v45, 0xbfb8aa3b, v41
	v_exp_f32_e32 v44, v44
	v_exp_f32_e32 v45, v45
	s_nop 0
	v_pk_add_f32 v[44:45], v[44:45], 1.0 op_sel_hi:[1,0]
	v_rcp_f32_e32 v46, v84
	s_nop 0
	v_mul_f32_e32 v42, v42, v46
	ds_write2_b32 v53, v42, v43 offset0:195 offset1:196
	v_pk_fma_f32 v[38:39], v[14:15], v[38:39], 0 op_sel_hi:[1,1,0]
	v_pk_fma_f32 v[38:39], v[18:19], v[36:37], v[38:39]
	v_pk_fma_f32 v[38:39], v[22:23], v[24:25], v[38:39]
	v_rcp_f32_e32 v42, v45
	s_nop 0
	v_mul_f32_e32 v41, v41, v42
	v_pk_fma_f32 v[38:39], v[16:17], v[26:27], v[38:39]
	v_pk_fma_f32 v[38:39], v[20:21], v[32:33], v[38:39]
	v_mul_f32_e32 v42, 0xbfb8aa3b, v38
	v_mul_f32_e32 v43, 0xbfb8aa3b, v39
	v_exp_f32_e32 v42, v42
	v_exp_f32_e32 v43, v43
	s_nop 0
	v_pk_add_f32 v[42:43], v[42:43], 1.0 op_sel_hi:[1,0]
	v_rcp_f32_e32 v45, v44
	s_nop 0
	v_mul_f32_e32 v40, v40, v45
	v_pk_fma_f32 v[36:37], v[14:15], v[36:37], 0 op_sel_hi:[1,1,0]
	v_pk_fma_f32 v[36:37], v[18:19], v[24:25], v[36:37]
	v_pk_fma_f32 v[36:37], v[22:23], v[26:27], v[36:37]
	v_pk_fma_f32 v[36:37], v[16:17], v[32:33], v[36:37]
	v_rcp_f32_e32 v44, v43
	s_nop 0
	v_mul_f32_e32 v39, v39, v44
	v_pk_fma_f32 v[36:37], v[20:21], v[34:35], v[36:37]
	v_mul_f32_e32 v44, 0xbfb8aa3b, v36
	v_mul_f32_e32 v45, 0xbfb8aa3b, v37
	v_exp_f32_e32 v44, v44
	v_exp_f32_e32 v45, v45
	s_nop 0
	v_pk_add_f32 v[44:45], v[44:45], 1.0 op_sel_hi:[1,0]
	v_add_u32_e32 v82, 0x514, v53
	v_rcp_f32_e32 v43, v42
	s_nop 0
	v_mul_f32_e32 v38, v38, v43
	ds_write2_b32 v82, v38, v39 offset1:1
	v_pk_fma_f32 v[14:15], v[14:15], v[24:25], 0 op_sel_hi:[1,1,0]
	v_pk_fma_f32 v[14:15], v[18:19], v[26:27], v[14:15]
	v_pk_fma_f32 v[14:15], v[22:23], v[32:33], v[14:15]
	v_pk_fma_f32 v[14:15], v[16:17], v[34:35], v[14:15]
	v_pk_fma_f32 v[14:15], v[20:21], v[30:31], v[14:15]
	v_mul_f32_e32 v16, 0xbfb8aa3b, v14
	v_mul_f32_e32 v17, 0xbfb8aa3b, v15
	v_exp_f32_e32 v16, v16
	v_exp_f32_e32 v17, v17
	v_rcp_f32_e32 v38, v45
	s_nop 0
	v_mul_f32_e32 v37, v37, v38
	v_pk_add_f32 v[16:17], v[16:17], 1.0 op_sel_hi:[1,0]
	v_rcp_f32_e32 v18, v44
	s_nop 0
	v_mul_f32_e32 v36, v36, v18
	v_rcp_f32_e32 v18, v17
	s_nop 0
	v_mul_f32_e32 v15, v15, v18
	v_add_u32_e32 v67, v0, v1
	v_rcp_f32_e32 v17, v16
	s_nop 0
	v_mul_f32_e32 v14, v14, v17
	ds_write2_b64 v53, v[40:41], v[36:37] offset0:130 offset1:195
	ds_write2_b32 v67, v14, v15 offset1:1
	s_waitcnt lgkmcnt(0)
	s_barrier
	ds_read2_b32 v[14:15], v66 offset1:1
	ds_read2_b32 v[16:17], v66 offset0:2 offset1:3
	ds_read2_b32 v[18:19], v66 offset0:4 offset1:5
	ds_read2_b32 v[20:21], v66 offset0:6 offset1:7
	v_cmp_eq_u32_e64 s[0:1], 0, v76
	s_waitcnt lgkmcnt(3)
	v_mul_f32_e32 v22, v15, v15
	v_fmac_f32_e32 v22, v14, v14
	s_waitcnt lgkmcnt(2)
	v_fmac_f32_e32 v22, v16, v16
	v_fmac_f32_e32 v22, v17, v17
	ds_read2_b32 v[14:15], v66 offset0:8 offset1:9
	s_waitcnt lgkmcnt(2)
	v_fmac_f32_e32 v22, v18, v18
	v_fmac_f32_e32 v22, v19, v19
	s_waitcnt lgkmcnt(1)
	v_fmac_f32_e32 v22, v20, v20
	v_fmac_f32_e32 v22, v21, v21
	ds_read2_b32 v[16:17], v66 offset0:10 offset1:11
	ds_read2_b32 v[18:19], v66 offset0:12 offset1:13
	ds_read2_b32 v[20:21], v66 offset0:14 offset1:15
	s_waitcnt lgkmcnt(3)
	v_fmac_f32_e32 v22, v14, v14
	v_fmac_f32_e32 v22, v15, v15
	s_waitcnt lgkmcnt(2)
	v_fmac_f32_e32 v22, v16, v16
	v_fmac_f32_e32 v22, v17, v17
	v_and_b32_e32 v15, 0xffffffc0, v49
	s_waitcnt lgkmcnt(1)
	v_fmac_f32_e32 v22, v18, v18
	v_xor_b32_e32 v14, 1, v49
	v_add_u32_e32 v50, 64, v15
	v_fmac_f32_e32 v22, v19, v19
	v_cmp_lt_i32_e32 vcc, v14, v50
	s_waitcnt lgkmcnt(0)
	v_fmac_f32_e32 v22, v20, v20
	v_fmac_f32_e32 v22, v21, v21
	v_cndmask_b32_e32 v14, v49, v14, vcc
	v_lshlrev_b32_e32 v83, 2, v14
	ds_bpermute_b32 v14, v83, v22
	v_xor_b32_e32 v15, 2, v49
	v_cmp_lt_i32_e32 vcc, v15, v50
	v_lshlrev_b32_e32 v47, 2, v51
	s_waitcnt lgkmcnt(0)
	v_add_f32_e32 v14, v22, v14
	v_cndmask_b32_e32 v15, v49, v15, vcc
	v_lshlrev_b32_e32 v84, 2, v15
	ds_bpermute_b32 v15, v84, v14
	s_and_saveexec_b64 s[2:3], s[0:1]
	s_cbranch_execz .LBB0_513
	s_waitcnt lgkmcnt(0)
	v_add_f32_e32 v14, v14, v15
	v_add_f32_e32 v14, 0x358637bd, v14
	v_mul_f32_e32 v15, 0x4b800000, v14
	v_cmp_gt_f32_e32 vcc, s40, v14
	s_nop 1
	v_cndmask_b32_e32 v14, v14, v15, vcc
	v_rsq_f32_e32 v14, v14
	s_nop 0
	v_mul_f32_e32 v15, 0x45800000, v14
	v_cndmask_b32_e32 v14, v14, v15, vcc
	v_mul_f32_e32 v14, 0x3e000000, v14
	ds_write_b32 v47, v14 offset:61952

.LBB0_516:
	s_or_b64 exec, exec, s[2:3]
	s_barrier
	global_load_dwordx2 v[22:23], v[2:3], off offset:1536
	global_load_dwordx2 v[24:25], v[4:5], off offset:2048
	s_nop 0
	global_load_dwordx2 v[10:11], v[10:11], off offset:2560
	s_nop 0
	global_load_dwordx2 v[26:27], v[6:7], off offset:3072
	global_load_dwordx2 v[30:31], v[8:9], off offset:3584
	v_lshlrev_b32_e32 v40, 16, v69
	v_and_b32_e32 v41, 0xffff0000, v69
	v_lshlrev_b32_e32 v44, 16, v68
	v_and_b32_e32 v45, 0xffff0000, v68
	v_lshlrev_b32_e32 v42, 16, v71
	v_and_b32_e32 v43, 0xffff0000, v71
	v_lshlrev_b32_e32 v38, 16, v70
	v_and_b32_e32 v39, 0xffff0000, v70
	v_lshlrev_b32_e32 v36, 16, v73
	v_and_b32_e32 v37, 0xffff0000, v73
	v_lshlrev_b32_e32 v34, 16, v72
	v_and_b32_e32 v35, 0xffff0000, v72
	v_lshlrev_b32_e32 v12, 16, v74
	v_and_b32_e32 v13, 0xffff0000, v74
	v_lshlrev_b32_e32 v32, 16, v75
	v_and_b32_e32 v33, 0xffff0000, v75
	v_lshlrev_b32_e32 v14, 16, v79
	v_and_b32_e32 v15, 0xffff0000, v79
	v_lshlrev_b32_e32 v18, 16, v78
	v_and_b32_e32 v19, 0xffff0000, v78
	v_lshlrev_b32_e32 v20, 16, v81
	v_and_b32_e32 v21, 0xffff0000, v81
	v_lshlrev_b32_e32 v16, 16, v80
	v_and_b32_e32 v17, 0xffff0000, v80
	s_waitcnt vmcnt(4)
	v_pk_fma_f32 v[40:41], v[22:23], v[40:41], 0 op_sel_hi:[1,1,0]
	s_waitcnt vmcnt(3)
	v_pk_fma_f32 v[40:41], v[24:25], v[44:45], v[40:41]
	v_pk_fma_f32 v[44:45], v[22:23], v[44:45], 0 op_sel_hi:[1,1,0]
	s_waitcnt vmcnt(2)
	v_pk_fma_f32 v[40:41], v[10:11], v[42:43], v[40:41]
	v_pk_fma_f32 v[44:45], v[24:25], v[42:43], v[44:45]
	s_waitcnt vmcnt(1)
	v_pk_fma_f32 v[40:41], v[26:27], v[38:39], v[40:41]
	v_pk_fma_f32 v[44:45], v[10:11], v[38:39], v[44:45]
	s_waitcnt vmcnt(0)
	v_pk_fma_f32 v[40:41], v[30:31], v[36:37], v[40:41]
	v_pk_fma_f32 v[44:45], v[26:27], v[36:37], v[44:45]
	v_mul_f32_e32 v68, 0xbfb8aa3b, v40
	v_mul_f32_e32 v69, 0xbfb8aa3b, v41
	v_exp_f32_e32 v68, v68
	v_exp_f32_e32 v69, v69
	v_pk_fma_f32 v[44:45], v[30:31], v[34:35], v[44:45]
	v_pk_fma_f32 v[42:43], v[22:23], v[42:43], 0 op_sel_hi:[1,1,0]
	v_pk_add_f32 v[68:69], v[68:69], 1.0 op_sel_hi:[1,0]
	s_nop 0
	v_pk_fma_f32 v[42:43], v[24:25], v[38:39], v[42:43]
	v_pk_fma_f32 v[38:39], v[22:23], v[38:39], 0 op_sel_hi:[1,1,0]
	v_pk_fma_f32 v[42:43], v[10:11], v[36:37], v[42:43]
	v_rcp_f32_e32 v70, v69
	s_nop 0
	v_mul_f32_e32 v41, v41, v70
	v_pk_fma_f32 v[42:43], v[26:27], v[34:35], v[42:43]
	v_pk_fma_f32 v[38:39], v[24:25], v[36:37], v[38:39]
	v_pk_fma_f32 v[42:43], v[30:31], v[32:33], v[42:43]
	v_rcp_f32_e32 v69, v68
	s_nop 0
	v_mul_f32_e32 v40, v40, v69
	v_mul_f32_e32 v68, 0xbfb8aa3b, v44
	v_mul_f32_e32 v69, 0xbfb8aa3b, v45
	v_exp_f32_e32 v68, v68
	v_exp_f32_e32 v69, v69
	v_pk_fma_f32 v[38:39], v[10:11], v[34:35], v[38:39]
	v_pk_fma_f32 v[36:37], v[22:23], v[36:37], 0 op_sel_hi:[1,1,0]
	v_pk_fma_f32 v[38:39], v[26:27], v[32:33], v[38:39]
	v_pk_add_f32 v[68:69], v[68:69], 1.0 op_sel_hi:[1,0]
	v_pk_fma_f32 v[38:39], v[30:31], v[12:13], v[38:39]
	v_pk_fma_f32 v[36:37], v[24:25], v[34:35], v[36:37]
	v_pk_fma_f32 v[34:35], v[22:23], v[34:35], 0 op_sel_hi:[1,1,0]
	v_pk_fma_f32 v[36:37], v[10:11], v[32:33], v[36:37]
	v_rcp_f32_e32 v70, v69
	s_nop 0
	v_mul_f32_e32 v45, v45, v70
	v_pk_fma_f32 v[36:37], v[26:27], v[12:13], v[36:37]
	v_pk_fma_f32 v[34:35], v[24:25], v[32:33], v[34:35]
	v_pk_fma_f32 v[36:37], v[30:31], v[14:15], v[36:37]
	v_rcp_f32_e32 v69, v68
	s_nop 0
	v_mul_f32_e32 v44, v44, v69
	ds_write2_b32 v53, v44, v45 offset0:65 offset1:66
	v_mul_f32_e32 v44, 0xbfb8aa3b, v42
	v_mul_f32_e32 v45, 0xbfb8aa3b, v43
	v_exp_f32_e32 v44, v44
	v_exp_f32_e32 v45, v45
	v_pk_fma_f32 v[34:35], v[10:11], v[12:13], v[34:35]
	v_pk_fma_f32 v[32:33], v[22:23], v[32:33], 0 op_sel_hi:[1,1,0]
	v_pk_fma_f32 v[34:35], v[26:27], v[14:15], v[34:35]
	v_pk_add_f32 v[44:45], v[44:45], 1.0 op_sel_hi:[1,0]
	v_pk_fma_f32 v[34:35], v[30:31], v[18:19], v[34:35]
	v_pk_fma_f32 v[32:33], v[24:25], v[12:13], v[32:33]
	v_pk_fma_f32 v[12:13], v[22:23], v[12:13], 0 op_sel_hi:[1,1,0]
	v_pk_fma_f32 v[32:33], v[10:11], v[14:15], v[32:33]
	v_rcp_f32_e32 v68, v45
	s_nop 0
	v_mul_f32_e32 v43, v43, v68
	v_pk_fma_f32 v[32:33], v[26:27], v[18:19], v[32:33]
	v_pk_fma_f32 v[12:13], v[24:25], v[14:15], v[12:13]
	v_pk_fma_f32 v[32:33], v[30:31], v[20:21], v[32:33]
	v_rcp_f32_e32 v45, v44
	s_nop 0
	v_mul_f32_e32 v42, v42, v45
	ds_write2_b64 v53, v[40:41], v[42:43] offset1:65
	v_mul_f32_e32 v40, 0xbfb8aa3b, v38
	v_mul_f32_e32 v41, 0xbfb8aa3b, v39
	v_exp_f32_e32 v40, v40
	v_exp_f32_e32 v41, v41
	v_pk_fma_f32 v[10:11], v[10:11], v[18:19], v[12:13]
	v_pk_add_f32 v[40:41], v[40:41], 1.0 op_sel_hi:[1,0]
	s_nop 0
	v_pk_fma_f32 v[10:11], v[26:27], v[20:21], v[10:11]
	v_rcp_f32_e32 v42, v41
	s_nop 0
	v_mul_f32_e32 v39, v39, v42
	v_pk_fma_f32 v[10:11], v[30:31], v[16:17], v[10:11]
	v_rcp_f32_e32 v41, v40
	s_nop 0
	v_mul_f32_e32 v38, v38, v41
	ds_write2_b32 v53, v38, v39 offset0:195 offset1:196
	v_mul_f32_e32 v38, 0xbfb8aa3b, v36
	v_mul_f32_e32 v39, 0xbfb8aa3b, v37
	v_exp_f32_e32 v38, v38
	v_exp_f32_e32 v39, v39
	v_mul_f32_e32 v12, 0xbfb8aa3b, v10
	v_mul_f32_e32 v13, 0xbfb8aa3b, v11
	v_exp_f32_e32 v12, v12
	v_pk_add_f32 v[38:39], v[38:39], 1.0 op_sel_hi:[1,0]
	v_exp_f32_e32 v13, v13
	s_nop 0
	v_pk_add_f32 v[12:13], v[12:13], 1.0 op_sel_hi:[1,0]
	v_rcp_f32_e32 v40, v39
	s_nop 0
	v_mul_f32_e32 v37, v37, v40
	v_rcp_f32_e32 v39, v38
	s_nop 0
	v_mul_f32_e32 v36, v36, v39
	v_mul_f32_e32 v38, 0xbfb8aa3b, v34
	v_mul_f32_e32 v39, 0xbfb8aa3b, v35
	v_exp_f32_e32 v38, v38
	v_exp_f32_e32 v39, v39
	s_nop 0
	v_pk_add_f32 v[38:39], v[38:39], 1.0 op_sel_hi:[1,0]
	s_nop 0
	s_nop 0
	v_rcp_f32_e32 v40, v39
	s_nop 0
	v_mul_f32_e32 v35, v35, v40
	s_nop 0
	v_rcp_f32_e32 v39, v38
	s_nop 0
	v_mul_f32_e32 v34, v34, v39
	ds_write2_b32 v82, v34, v35 offset1:1
	v_mul_f32_e32 v34, 0xbfb8aa3b, v32
	v_mul_f32_e32 v35, 0xbfb8aa3b, v33
	v_exp_f32_e32 v34, v34
	v_exp_f32_e32 v35, v35
	s_nop 0
	v_pk_add_f32 v[34:35], v[34:35], 1.0 op_sel_hi:[1,0]
	s_nop 0
	s_nop 0
	v_rcp_f32_e32 v38, v35
	s_nop 0
	v_mul_f32_e32 v33, v33, v38
	s_nop 0
	v_rcp_f32_e32 v14, v13
	s_nop 0
	v_mul_f32_e32 v11, v11, v14
	v_rcp_f32_e32 v35, v34
	s_nop 0
	v_mul_f32_e32 v32, v32, v35
	ds_write2_b64 v53, v[36:37], v[32:33] offset0:130 offset1:195
	v_rcp_f32_e32 v13, v12
	s_nop 0
	v_mul_f32_e32 v10, v10, v13
	ds_write2_b32 v67, v10, v11 offset1:1
	s_waitcnt lgkmcnt(0)
	s_barrier
	ds_read2_b32 v[10:11], v66 offset1:1
	s_waitcnt lgkmcnt(0)
	v_mul_f32_e32 v12, v11, v11
	v_fmac_f32_e32 v12, v10, v10
	ds_read2_b32 v[10:11], v66 offset0:2 offset1:3
	s_waitcnt lgkmcnt(0)
	v_fmac_f32_e32 v12, v10, v10
	v_fmac_f32_e32 v12, v11, v11
	ds_read2_b32 v[10:11], v66 offset0:4 offset1:5
	s_waitcnt lgkmcnt(0)
	v_fmac_f32_e32 v12, v10, v10
	v_fmac_f32_e32 v12, v11, v11
	ds_read2_b32 v[10:11], v66 offset0:6 offset1:7
	s_waitcnt lgkmcnt(0)
	v_fmac_f32_e32 v12, v10, v10
	v_fmac_f32_e32 v12, v11, v11
	ds_read2_b32 v[10:11], v66 offset0:8 offset1:9
	s_waitcnt lgkmcnt(0)
	v_fmac_f32_e32 v12, v10, v10
	v_fmac_f32_e32 v12, v11, v11
	ds_read2_b32 v[10:11], v66 offset0:10 offset1:11
	s_waitcnt lgkmcnt(0)
	v_fmac_f32_e32 v12, v10, v10
	v_fmac_f32_e32 v12, v11, v11
	ds_read2_b32 v[10:11], v66 offset0:12 offset1:13
	s_waitcnt lgkmcnt(0)
	v_fmac_f32_e32 v12, v10, v10
	v_fmac_f32_e32 v12, v11, v11
	ds_read2_b32 v[10:11], v66 offset0:14 offset1:15
	s_waitcnt lgkmcnt(0)
	v_fmac_f32_e32 v12, v10, v10
	v_fmac_f32_e32 v12, v11, v11
	ds_bpermute_b32 v10, v83, v12
	s_waitcnt lgkmcnt(0)
	v_add_f32_e32 v10, v12, v10
	ds_bpermute_b32 v11, v84, v10
	s_and_saveexec_b64 s[2:3], s[0:1]
	s_cbranch_execz .LBB0_518
	s_waitcnt lgkmcnt(0)
	v_add_f32_e32 v10, v10, v11
	v_add_f32_e32 v10, 0x358637bd, v10
	v_mul_f32_e32 v11, 0x4b800000, v10
	v_cmp_gt_f32_e32 vcc, s40, v10
	s_nop 1
	v_cndmask_b32_e32 v10, v10, v11, vcc
	v_rsq_f32_e32 v10, v10
	s_nop 0
	v_mul_f32_e32 v11, 0x45800000, v10
	v_cndmask_b32_e32 v10, v10, v11, vcc
	ds_write_b32 v47, v10 offset:61952

.LBB0_521:
	s_or_b64 exec, exec, s[0:1]
	s_movk_i32 s0, 0x5000
	s_waitcnt lgkmcnt(0)
	s_barrier
	global_load_dwordx2 v[20:21], v[2:3], off offset:3072
	s_nop 0
	global_load_dwordx2 v[4:5], v[4:5], off offset:3584
	s_nop 0
	global_load_dwordx2 v[6:7], v[6:7], off
	s_nop 0
	global_load_dwordx2 v[8:9], v[8:9], off offset:512
	v_add_co_u32_e32 v2, vcc, s0, v2
	v_lshlrev_b32_e32 v34, 16, v55
	s_nop 0
	v_addc_co_u32_e32 v3, vcc, 0, v3, vcc
	global_load_dwordx2 v[2:3], v[2:3], off offset:1024
	v_and_b32_e32 v35, 0xffff0000, v55
	v_lshlrev_b32_e32 v36, 16, v54
	v_and_b32_e32 v37, 0xffff0000, v54
	v_lshlrev_b32_e32 v32, 16, v57
	v_and_b32_e32 v33, 0xffff0000, v57
	v_lshlrev_b32_e32 v30, 16, v56
	v_and_b32_e32 v31, 0xffff0000, v56
	v_lshlrev_b32_e32 v26, 16, v59
	v_and_b32_e32 v27, 0xffff0000, v59
	v_lshlrev_b32_e32 v24, 16, v58
	v_and_b32_e32 v25, 0xffff0000, v58
	v_lshlrev_b32_e32 v22, 16, v61
	v_and_b32_e32 v23, 0xffff0000, v61
	v_lshlrev_b32_e32 v10, 16, v60
	v_and_b32_e32 v11, 0xffff0000, v60
	v_lshlrev_b32_e32 v12, 16, v63
	v_and_b32_e32 v13, 0xffff0000, v63
	v_lshlrev_b32_e32 v16, 16, v62
	v_and_b32_e32 v17, 0xffff0000, v62
	v_lshlrev_b32_e32 v18, 16, v65
	v_and_b32_e32 v19, 0xffff0000, v65
	v_lshlrev_b32_e32 v14, 16, v64
	v_and_b32_e32 v15, 0xffff0000, v64
	v_lshrrev_b32_e32 v185, 5, v48
	s_waitcnt vmcnt(4)
	v_pk_fma_f32 v[34:35], v[20:21], v[34:35], 0 op_sel_hi:[1,1,0]
	s_waitcnt vmcnt(3)
	v_pk_fma_f32 v[34:35], v[4:5], v[36:37], v[34:35]
	v_pk_fma_f32 v[36:37], v[20:21], v[36:37], 0 op_sel_hi:[1,1,0]
	s_waitcnt vmcnt(2)
	v_pk_fma_f32 v[34:35], v[6:7], v[32:33], v[34:35]
	v_pk_fma_f32 v[36:37], v[4:5], v[32:33], v[36:37]
	s_waitcnt vmcnt(1)
	v_pk_fma_f32 v[34:35], v[8:9], v[30:31], v[34:35]
	v_pk_fma_f32 v[36:37], v[6:7], v[30:31], v[36:37]
	v_pk_fma_f32 v[32:33], v[20:21], v[32:33], 0 op_sel_hi:[1,1,0]
	v_pk_fma_f32 v[36:37], v[8:9], v[26:27], v[36:37]
	s_waitcnt vmcnt(0)
	v_pk_fma_f32 v[34:35], v[2:3], v[26:27], v[34:35]
	v_pk_fma_f32 v[36:37], v[2:3], v[24:25], v[36:37]
	v_mul_f32_e32 v38, 0xbfb8aa3b, v34
	v_mul_f32_e32 v39, 0xbfb8aa3b, v35
	v_exp_f32_e32 v38, v38
	v_exp_f32_e32 v39, v39
	v_pk_fma_f32 v[32:33], v[4:5], v[30:31], v[32:33]
	v_pk_fma_f32 v[30:31], v[20:21], v[30:31], 0 op_sel_hi:[1,1,0]
	v_pk_fma_f32 v[32:33], v[6:7], v[26:27], v[32:33]
	v_pk_add_f32 v[38:39], v[38:39], 1.0 op_sel_hi:[1,0]
	v_pk_fma_f32 v[32:33], v[8:9], v[24:25], v[32:33]
	v_pk_fma_f32 v[32:33], v[2:3], v[22:23], v[32:33]
	v_pk_fma_f32 v[30:31], v[4:5], v[26:27], v[30:31]
	v_pk_fma_f32 v[26:27], v[20:21], v[26:27], 0 op_sel_hi:[1,1,0]
	v_rcp_f32_e32 v40, v39
	s_nop 0
	v_mul_f32_e32 v35, v35, v40
	v_pk_fma_f32 v[30:31], v[6:7], v[24:25], v[30:31]
	v_pk_fma_f32 v[26:27], v[4:5], v[24:25], v[26:27]
	v_pk_fma_f32 v[30:31], v[8:9], v[22:23], v[30:31]
	v_rcp_f32_e32 v39, v38
	s_nop 0
	v_mul_f32_e32 v34, v34, v39
	v_mul_f32_e32 v38, 0xbfb8aa3b, v36
	v_mul_f32_e32 v39, 0xbfb8aa3b, v37
	v_exp_f32_e32 v38, v38
	v_exp_f32_e32 v39, v39
	v_pk_fma_f32 v[30:31], v[2:3], v[10:11], v[30:31]
	v_pk_fma_f32 v[26:27], v[6:7], v[22:23], v[26:27]
	v_pk_fma_f32 v[24:25], v[20:21], v[24:25], 0 op_sel_hi:[1,1,0]
	v_pk_add_f32 v[38:39], v[38:39], 1.0 op_sel_hi:[1,0]
	v_pk_fma_f32 v[26:27], v[8:9], v[10:11], v[26:27]
	v_pk_fma_f32 v[26:27], v[2:3], v[12:13], v[26:27]
	v_pk_fma_f32 v[24:25], v[4:5], v[22:23], v[24:25]
	v_pk_fma_f32 v[22:23], v[20:21], v[22:23], 0 op_sel_hi:[1,1,0]
	v_rcp_f32_e32 v40, v39
	s_nop 0
	v_mul_f32_e32 v37, v37, v40
	v_pk_fma_f32 v[24:25], v[6:7], v[10:11], v[24:25]
	v_pk_fma_f32 v[22:23], v[4:5], v[10:11], v[22:23]
	v_pk_fma_f32 v[24:25], v[8:9], v[12:13], v[24:25]
	v_rcp_f32_e32 v39, v38
	s_nop 0
	v_mul_f32_e32 v36, v36, v39
	v_add_u32_e32 v38, 0x4204, v53
	ds_write2_b32 v38, v36, v37 offset1:1
	v_mul_f32_e32 v36, 0xbfb8aa3b, v32
	v_mul_f32_e32 v37, 0xbfb8aa3b, v33
	v_exp_f32_e32 v36, v36
	v_exp_f32_e32 v37, v37
	v_pk_fma_f32 v[24:25], v[2:3], v[16:17], v[24:25]
	v_pk_fma_f32 v[22:23], v[6:7], v[12:13], v[22:23]
	v_pk_fma_f32 v[10:11], v[20:21], v[10:11], 0 op_sel_hi:[1,1,0]
	v_pk_add_f32 v[36:37], v[36:37], 1.0 op_sel_hi:[1,0]
	v_pk_fma_f32 v[22:23], v[8:9], v[16:17], v[22:23]
	v_pk_fma_f32 v[22:23], v[2:3], v[18:19], v[22:23]
	v_pk_fma_f32 v[4:5], v[4:5], v[12:13], v[10:11]
	v_rcp_f32_e32 v38, v37
	s_nop 0
	v_mul_f32_e32 v33, v33, v38
	v_pk_fma_f32 v[4:5], v[6:7], v[16:17], v[4:5]
	v_rcp_f32_e32 v37, v36
	s_nop 0
	v_mul_f32_e32 v32, v32, v37
	v_add_u32_e32 v36, 0x4000, v53
	ds_write2_b64 v36, v[34:35], v[32:33] offset0:32 offset1:97
	v_mul_f32_e32 v32, 0xbfb8aa3b, v30
	v_mul_f32_e32 v33, 0xbfb8aa3b, v31
	v_exp_f32_e32 v32, v32
	v_exp_f32_e32 v33, v33
	v_pk_fma_f32 v[4:5], v[8:9], v[18:19], v[4:5]
	v_lshlrev_b32_e32 v41, 2, v185
	v_pk_fma_f32 v[2:3], v[2:3], v[14:15], v[4:5]
	v_pk_add_f32 v[32:33], v[32:33], 1.0 op_sel_hi:[1,0]
	v_mul_f32_e32 v4, 0xbfb8aa3b, v2
	v_mul_f32_e32 v5, 0xbfb8aa3b, v3
	v_exp_f32_e32 v4, v4
	v_exp_f32_e32 v5, v5
	v_rcp_f32_e32 v34, v33
	s_nop 0
	v_mul_f32_e32 v31, v31, v34
	v_pk_add_f32 v[4:5], v[4:5], 1.0 op_sel_hi:[1,0]
	v_xor_b32_e32 v157, 63, v41
	v_rcp_f32_e32 v33, v32
	s_nop 0
	v_mul_f32_e32 v30, v30, v33
	v_add_u32_e32 v32, 0x440c, v53
	ds_write2_b32 v32, v30, v31 offset1:1
	v_mul_f32_e32 v30, 0xbfb8aa3b, v26
	v_mul_f32_e32 v31, 0xbfb8aa3b, v27
	v_exp_f32_e32 v30, v30
	v_exp_f32_e32 v31, v31
	v_xor_b32_e32 v155, 4, v41
	v_pk_add_f32 v[30:31], v[30:31], 1.0 op_sel_hi:[1,0]
	s_nop 0
	v_rcp_f32_e32 v32, v31
	s_nop 0
	v_mul_f32_e32 v27, v27, v32
	s_nop 0
	v_rcp_f32_e32 v31, v30
	s_nop 0
	v_mul_f32_e32 v26, v26, v31
	v_mul_f32_e32 v30, 0xbfb8aa3b, v24
	v_mul_f32_e32 v31, 0xbfb8aa3b, v25
	v_exp_f32_e32 v30, v30
	v_exp_f32_e32 v31, v31
	s_nop 0
	v_pk_add_f32 v[30:31], v[30:31], 1.0 op_sel_hi:[1,0]
	s_nop 0
	s_nop 0
	v_rcp_f32_e32 v32, v31
	s_nop 0
	v_mul_f32_e32 v25, v25, v32
	s_nop 0
	v_rcp_f32_e32 v31, v30
	s_nop 0
	v_mul_f32_e32 v24, v24, v31
	v_add_u32_e32 v30, 0x4614, v53
	ds_write2_b32 v30, v24, v25 offset1:1
	v_mul_f32_e32 v24, 0xbfb8aa3b, v22
	v_mul_f32_e32 v25, 0xbfb8aa3b, v23
	v_exp_f32_e32 v24, v24
	v_exp_f32_e32 v25, v25
	s_nop 0
	v_pk_add_f32 v[24:25], v[24:25], 1.0 op_sel_hi:[1,0]
	s_nop 0
	s_nop 0
	v_rcp_f32_e32 v30, v25
	s_nop 0
	v_mul_f32_e32 v23, v23, v30
	s_nop 0
	v_rcp_f32_e32 v6, v5
	s_nop 0
	v_mul_f32_e32 v3, v3, v6
	s_movk_i32 s0, 0x4100
	v_rcp_f32_e32 v25, v24
	s_nop 0
	v_mul_f32_e32 v22, v22, v25
	v_add3_u32 v0, v0, v1, s0
	v_rcp_f32_e32 v5, v4
	s_nop 0
	v_mul_f32_e32 v2, v2, v5
	ds_write2_b64 v36, v[26:27], v[22:23] offset0:162 offset1:227
	ds_write2_b32 v0, v2, v3 offset1:1
	v_lshlrev_b32_e32 v0, 4, v52
	v_and_b32_e32 v10, 48, v0
	v_mul_u32_u24_e32 v0, 0x48, v10
	v_lshlrev_b32_e32 v0, 1, v0
	v_lshl_add_u32 v7, v51, 1, v0
	s_waitcnt lgkmcnt(0)
	s_barrier
	ds_read_u16 v0, v7 offset:33280
	ds_read_u16 v1, v7 offset:33424
	s_mul_i32 s1, s8, 0x56
	s_bfe_u32 s2, s1, 0x1000f
	s_bfe_u32 s1, s1, 0x80008
	s_add_i32 s2, s1, s2
	s_waitcnt lgkmcnt(0)
	v_lshl_or_b32 v0, v1, 16, v0
	ds_read_u16 v1, v7 offset:33568
	ds_read_u16 v2, v7 offset:33712
	s_ashr_i32 s0, s10, 5
	s_sext_i32_i8 s1, s2
	s_add_i32 s0, s0, s1
	s_ashr_i32 s1, s0, 31
	s_waitcnt lgkmcnt(0)
	v_lshl_or_b32 v1, v2, 16, v1
	ds_read_u16 v2, v7 offset:33856
	ds_read_u16 v3, v7 offset:34000
	s_lshl_b64 s[0:1], s[0:1], 16
	s_add_u32 s3, s64, s0
	s_mul_i32 s2, s2, 3
	s_addc_u32 s4, s65, s1
	s_waitcnt lgkmcnt(0)
	v_lshl_or_b32 v2, v3, 16, v2
	ds_read_u16 v3, v7 offset:34144
	ds_read_u16 v4, v7 offset:34288
	s_sub_i32 s0, s8, s2
	s_sext_i32_i8 s0, s0
	s_lshl_b32 s0, s0, 12
	s_ashr_i32 s1, s0, 31
	s_waitcnt lgkmcnt(0)
	v_lshl_or_b32 v3, v4, 16, v3
	ds_read_u16 v4, v7 offset:34432
	ds_read_u16 v5, v7 offset:34576
	s_lshl_b64 s[0:1], s[0:1], 1
	s_add_u32 s0, s3, s0
	s_addc_u32 s1, s4, s1
	v_lshlrev_b32_e32 v176, 1, v10
	s_waitcnt lgkmcnt(0)
	v_lshl_or_b32 v4, v5, 16, v4
	ds_read_u16 v5, v7 offset:34720
	ds_read_u16 v6, v7 offset:34864
	v_and_b32_e32 v26, 0xffffffe0, v51
	v_or_b32_e32 v36, v41, v26
	v_lshlrev_b32_e32 v37, 2, v36
	s_waitcnt lgkmcnt(0)
	v_lshl_or_b32 v5, v6, 16, v5
	ds_read_u16 v6, v7 offset:35008
	ds_read_u16 v8, v7 offset:35152
	s_waitcnt lgkmcnt(0)
	v_lshl_or_b32 v6, v8, 16, v6
	ds_read_u16 v8, v7 offset:35296
	ds_read_u16 v7, v7 offset:35440
	s_waitcnt lgkmcnt(0)
	v_lshl_or_b32 v7, v7, 16, v8
	v_lshlrev_b32_e32 v8, 6, v51
	v_ashrrev_i32_e32 v9, 31, v8
	v_lshl_add_u64 v[8:9], v[8:9], 1, s[0:1]
	v_lshl_add_u64 v[8:9], v[8:9], 0, v[176:177]
	s_mov_b64 s[0:1], 0xa000
	v_lshl_add_u64 v[10:11], v[8:9], 0, s[0:1]
	s_mov_b32 s0, 0xa000
	v_add_co_u32_e32 v8, vcc, s0, v8
	s_nop 1
	v_addc_co_u32_e32 v9, vcc, 0, v9, vcc
	global_store_dwordx4 v[8:9], v[0:3], off
	global_store_dwordx4 v[10:11], v[4:7], off offset:16
	s_nop 0
	v_or_b32_e32 v1, v26, v154
	v_lshlrev_b32_e32 v0, 4, v185
	v_mad_u64_u32 v[24:25], s[0:1], v1, s42, v[0:1]
	v_lshlrev_b32_e32 v1, 5, v29
	v_and_b32_e32 v176, 32, v1
	v_or_b32_e32 v33, v176, v154
	v_mad_u32_u24 v25, v33, s42, v0
	ds_read_b128 v[0:3], v24 offset:33280
	ds_read_b128 v[16:19], v24 offset:33312
	ds_read_b128 v[4:7], v25 offset:33280
	ds_read_b128 v[20:23], v25 offset:33312
	s_waitcnt lgkmcnt(1)
	v_mfma_f32_32x32x16_bf16 v[0:15], v[0:3], v[4:7], 0
	v_cmp_gt_i32_e32 vcc, v36, v33
	v_bitop3_b32 v38, v176, 63, v154 bitop3:0x36
	s_waitcnt lgkmcnt(0)
	v_mfma_f32_32x32x16_bf16 v[0:15], v[16:19], v[20:23], v[0:15]
	ds_read_b128 v[16:19], v24 offset:33344
	ds_read_b128 v[20:23], v25 offset:33344
	s_waitcnt lgkmcnt(0)
	v_mfma_f32_32x32x16_bf16 v[0:15], v[16:19], v[20:23], v[0:15]
	ds_read_b128 v[16:19], v24 offset:33376
	ds_read_b128 v[20:23], v25 offset:33376
	s_waitcnt lgkmcnt(0)
	v_mfma_f32_32x32x16_bf16 v[0:15], v[16:19], v[20:23], v[0:15]
	v_mul_i32_i24_e32 v16, 0xffffff74, v33
	v_mad_u32_u24 v16, v33, s42, v16
	v_lshlrev_b32_e32 v17, 1, v33
	ds_read2st64_b32 v[30:31], v16 offset0:240 offset1:241
	v_sub_u32_e32 v32, v16, v17
	ds_read_b128 v[16:19], v37 offset:61440
	ds_read_b128 v[20:23], v37 offset:60928
	ds_read_b128 v[24:27], v37 offset:61696
	ds_read_b128 v[42:45], v37 offset:61184
	s_waitcnt lgkmcnt(3)
	v_sub_f32_e32 v16, v16, v30
	v_mul_f32_e32 v16, 0x3fb8aa3b, v16
	v_exp_f32_e32 v16, v16
	s_waitcnt lgkmcnt(1)
	v_sub_f32_e32 v24, v24, v31
	v_mul_f32_e32 v24, 0x3fb8aa3b, v24
	v_exp_f32_e32 v24, v24
	v_mul_f32_e32 v16, v0, v16
	v_mul_f32_e64 v16, v16, -v20
	v_cvt_pk_bf16_f32 v16, v16, s0
	v_mul_f32_e32 v0, v0, v24
	v_cndmask_b32_e32 v16, 0, v16, vcc
	v_mad_u64_u32 v[34:35], s[0:1], v36, s42, v[32:33]
	ds_write_b16 v34, v16 offset:42496
	s_waitcnt lgkmcnt(1)
	v_mul_f32_e64 v0, v0, -v42
	v_sub_u32_e32 v16, 63, v36
	v_lshlrev_b32_e32 v32, 1, v38
	v_cvt_pk_bf16_f32 v0, v0, s0
	v_mad_u64_u32 v[38:39], s[0:1], v16, s42, v[32:33]
	v_sub_f32_e32 v16, v17, v30
	v_mul_f32_e32 v16, 0x3fb8aa3b, v16
	v_sub_f32_e32 v17, v25, v31
	v_exp_f32_e32 v16, v16
	v_mul_f32_e32 v17, 0x3fb8aa3b, v17
	v_exp_f32_e32 v17, v17
	v_cmp_lt_i32_e32 vcc, v36, v33
	v_mul_f32_e32 v16, v1, v16
	v_mul_f32_e64 v16, v16, -v21
	v_cndmask_b32_e32 v0, 0, v0, vcc
	v_mul_f32_e32 v1, v1, v17
	ds_write_b16 v38, v0 offset:51712
	v_or_b32_e32 v0, 1, v36
	v_cvt_pk_bf16_f32 v16, v16, s0
	v_mul_f32_e64 v1, v1, -v43
	v_cndmask_b32_e64 v16, v16, 0, vcc
	v_cmp_lt_i32_e32 vcc, v0, v33
	v_cvt_pk_bf16_f32 v1, v1, s0
	v_sub_u32_e32 v0, 63, v0
	ds_write_b16 v34, v16 offset:42640
	v_cndmask_b32_e32 v16, 0, v1, vcc
	v_mad_u64_u32 v[0:1], s[0:1], v0, s42, v[32:33]
	v_sub_f32_e32 v1, v18, v30
	v_mul_f32_e32 v1, 0x3fb8aa3b, v1
	v_exp_f32_e32 v1, v1
	ds_write_b16 v0, v16 offset:51712
	v_sub_f32_e32 v16, v26, v31
	v_mul_f32_e32 v16, 0x3fb8aa3b, v16
	v_exp_f32_e32 v16, v16
	v_mul_f32_e32 v1, v2, v1
	v_or_b32_e32 v0, 2, v36
	v_mul_f32_e64 v1, v1, -v22
	v_cmp_gt_i32_e32 vcc, v0, v33
	v_cvt_pk_bf16_f32 v1, v1, s0
	v_mul_f32_e32 v2, v2, v16
	v_cndmask_b32_e32 v1, 0, v1, vcc
	ds_write_b16 v34, v1 offset:42784
	v_mul_f32_e64 v1, v2, -v44
	v_cmp_lt_i32_e32 vcc, v0, v33
	v_cvt_pk_bf16_f32 v1, v1, s0
	v_sub_u32_e32 v0, 63, v0
	v_cndmask_b32_e32 v2, 0, v1, vcc
	v_mad_u64_u32 v[0:1], s[0:1], v0, s42, v[32:33]
	v_sub_f32_e32 v1, v19, v30
	v_mul_f32_e32 v1, 0x3fb8aa3b, v1
	v_exp_f32_e32 v1, v1
	ds_write_b16 v0, v2 offset:51712
	v_sub_f32_e32 v2, v27, v31
	v_mul_f32_e32 v2, 0x3fb8aa3b, v2
	v_exp_f32_e32 v2, v2
	v_mul_f32_e32 v1, v3, v1
	v_or_b32_e32 v0, 3, v36
	v_mul_f32_e64 v1, v1, -v23
	v_cmp_gt_i32_e32 vcc, v0, v33
	v_cvt_pk_bf16_f32 v1, v1, s0
	ds_read_b128 v[16:19], v37 offset:61472
	v_mul_f32_e32 v2, v3, v2
	v_cndmask_b32_e32 v1, 0, v1, vcc
	ds_write_b16 v34, v1 offset:42928
	v_mul_f32_e64 v1, v2, -v45
	v_cmp_lt_i32_e32 vcc, v0, v33
	v_cvt_pk_bf16_f32 v1, v1, s0
	v_sub_u32_e32 v0, 63, v0
	v_cndmask_b32_e32 v2, 0, v1, vcc
	v_mad_u64_u32 v[0:1], s[0:1], v0, s42, v[32:33]
	ds_write_b16 v0, v2 offset:51712
	s_waitcnt lgkmcnt(2)
	v_sub_f32_e32 v0, v16, v30
	v_mul_f32_e32 v0, 0x3fb8aa3b, v0
	v_exp_f32_e32 v0, v0
	v_or_b32_e32 v35, 8, v36
	v_cmp_gt_i32_e32 vcc, v35, v33
	v_mul_f32_e32 v16, v4, v0
	ds_read_b128 v[0:3], v37 offset:60960
	ds_read_b128 v[20:23], v37 offset:61728
	ds_read_b128 v[24:27], v37 offset:61216
	s_waitcnt lgkmcnt(2)
	v_mul_f32_e64 v0, v16, -v0
	s_waitcnt lgkmcnt(1)
	v_sub_f32_e32 v20, v20, v31
	v_mul_f32_e32 v20, 0x3fb8aa3b, v20
	v_exp_f32_e32 v20, v20
	v_cvt_pk_bf16_f32 v0, v0, s0
	v_cndmask_b32_e32 v0, 0, v0, vcc
	ds_write_b16 v34, v0 offset:43648
	v_mul_f32_e32 v4, v4, v20
	s_waitcnt lgkmcnt(1)
	v_mul_f32_e64 v0, v4, -v24
	v_sub_u32_e32 v4, 63, v35
	v_cvt_pk_bf16_f32 v0, v0, s0
	v_mad_u64_u32 v[38:39], s[0:1], v4, s42, v[32:33]
	v_sub_f32_e32 v4, v17, v30
	v_mul_f32_e32 v4, 0x3fb8aa3b, v4
	v_exp_f32_e32 v4, v4
	v_sub_f32_e32 v16, v21, v31
	v_mul_f32_e32 v16, 0x3fb8aa3b, v16
	v_cmp_lt_i32_e32 vcc, v35, v33
	v_exp_f32_e32 v16, v16
	v_mul_f32_e32 v4, v5, v4
	v_cndmask_b32_e32 v0, 0, v0, vcc
	ds_write_b16 v38, v0 offset:51712
	v_or_b32_e32 v0, 9, v36
	v_mul_f32_e64 v1, v4, -v1
	v_cmp_gt_i32_e32 vcc, v0, v33
	v_cvt_pk_bf16_f32 v1, v1, s0
	v_mul_f32_e32 v5, v5, v16
	v_cndmask_b32_e32 v1, 0, v1, vcc
	ds_write_b16 v34, v1 offset:43792
	v_mul_f32_e64 v1, v5, -v25
	v_cmp_lt_i32_e32 vcc, v0, v33
	v_cvt_pk_bf16_f32 v1, v1, s0
	v_sub_u32_e32 v0, 63, v0
	v_cndmask_b32_e32 v4, 0, v1, vcc
	v_mad_u64_u32 v[0:1], s[0:1], v0, s42, v[32:33]
	v_sub_f32_e32 v1, v18, v30
	v_mul_f32_e32 v1, 0x3fb8aa3b, v1
	v_exp_f32_e32 v1, v1
	ds_write_b16 v0, v4 offset:51712
	v_sub_f32_e32 v4, v22, v31
	v_mul_f32_e32 v4, 0x3fb8aa3b, v4
	v_exp_f32_e32 v4, v4
	v_mul_f32_e32 v1, v6, v1
	v_or_b32_e32 v0, 10, v36
	v_mul_f32_e64 v1, v1, -v2
	v_cmp_gt_i32_e32 vcc, v0, v33
	v_cvt_pk_bf16_f32 v1, v1, s0
	v_mul_f32_e32 v4, v6, v4
	v_cndmask_b32_e32 v1, 0, v1, vcc
	ds_write_b16 v34, v1 offset:43936
	v_mul_f32_e64 v1, v4, -v26
	v_cmp_lt_i32_e32 vcc, v0, v33
	v_cvt_pk_bf16_f32 v1, v1, s0
	v_sub_u32_e32 v0, 63, v0
	v_cndmask_b32_e32 v2, 0, v1, vcc
	v_mad_u64_u32 v[0:1], s[0:1], v0, s42, v[32:33]
	v_sub_f32_e32 v1, v19, v30
	v_mul_f32_e32 v1, 0x3fb8aa3b, v1
	v_exp_f32_e32 v1, v1
	ds_write_b16 v0, v2 offset:51712
	v_sub_f32_e32 v2, v23, v31
	v_mul_f32_e32 v2, 0x3fb8aa3b, v2
	v_exp_f32_e32 v2, v2
	v_mul_f32_e32 v1, v7, v1
	v_or_b32_e32 v0, 11, v36
	v_mul_f32_e64 v1, v1, -v3
	v_cmp_gt_i32_e32 vcc, v0, v33
	v_cvt_pk_bf16_f32 v1, v1, s0
	v_mul_f32_e32 v2, v7, v2
	v_cndmask_b32_e32 v1, 0, v1, vcc
	ds_write_b16 v34, v1 offset:44080
	v_mul_f32_e64 v1, v2, -v27
	v_cmp_lt_i32_e32 vcc, v0, v33
	v_cvt_pk_bf16_f32 v1, v1, s0
	v_sub_u32_e32 v0, 63, v0
	v_cndmask_b32_e32 v2, 0, v1, vcc
	v_mad_u64_u32 v[0:1], s[0:1], v0, s42, v[32:33]
	ds_write_b16 v0, v2 offset:51712
	ds_read_b128 v[0:3], v37 offset:61504
	ds_read_b128 v[4:7], v37 offset:60992
	ds_read_b128 v[16:19], v37 offset:61760
	ds_read_b128 v[20:23], v37 offset:61248
	v_or_b32_e32 v24, 16, v36
	v_cmp_gt_i32_e32 vcc, v24, v33
	s_waitcnt lgkmcnt(3)
	v_sub_f32_e32 v0, v0, v30
	v_mul_f32_e32 v0, 0x3fb8aa3b, v0
	v_exp_f32_e32 v0, v0
	s_waitcnt lgkmcnt(1)
	v_sub_f32_e32 v16, v16, v31
	v_mul_f32_e32 v16, 0x3fb8aa3b, v16
	v_exp_f32_e32 v16, v16
	v_mul_f32_e32 v0, v8, v0
	v_mul_f32_e64 v0, v0, -v4
	v_cvt_pk_bf16_f32 v0, v0, s0
	v_sub_f32_e32 v1, v1, v30
	v_mul_f32_e32 v8, v8, v16
	v_cndmask_b32_e32 v0, 0, v0, vcc
	v_mul_f32_e32 v1, 0x3fb8aa3b, v1
	ds_write_b16 v34, v0 offset:44800
	s_waitcnt lgkmcnt(1)
	v_mul_f32_e64 v0, v8, -v20
	v_sub_u32_e32 v4, 63, v24
	v_exp_f32_e32 v1, v1
	v_cmp_lt_i32_e32 vcc, v24, v33
	v_cvt_pk_bf16_f32 v0, v0, s0
	v_mad_u64_u32 v[24:25], s[0:1], v4, s42, v[32:33]
	v_sub_f32_e32 v4, v17, v31
	v_mul_f32_e32 v4, 0x3fb8aa3b, v4
	v_exp_f32_e32 v4, v4
	v_cndmask_b32_e32 v0, 0, v0, vcc
	v_mul_f32_e32 v1, v9, v1
	ds_write_b16 v24, v0 offset:51712
	v_or_b32_e32 v0, 17, v36
	v_mul_f32_e64 v1, v1, -v5
	v_cmp_gt_i32_e32 vcc, v0, v33
	v_cvt_pk_bf16_f32 v1, v1, s0
	v_mul_f32_e32 v4, v9, v4
	v_cndmask_b32_e32 v1, 0, v1, vcc
	ds_write_b16 v34, v1 offset:44944
	v_mul_f32_e64 v1, v4, -v21
	v_cmp_lt_i32_e32 vcc, v0, v33
	v_cvt_pk_bf16_f32 v1, v1, s0
	v_sub_u32_e32 v0, 63, v0
	v_cndmask_b32_e32 v4, 0, v1, vcc
	v_mad_u64_u32 v[0:1], s[0:1], v0, s42, v[32:33]
	v_sub_f32_e32 v1, v2, v30
	v_mul_f32_e32 v1, 0x3fb8aa3b, v1
	v_exp_f32_e32 v1, v1
	v_sub_f32_e32 v2, v18, v31
	v_mul_f32_e32 v2, 0x3fb8aa3b, v2
	v_exp_f32_e32 v2, v2
	v_mul_f32_e32 v1, v10, v1
	ds_write_b16 v0, v4 offset:51712
	v_or_b32_e32 v0, 18, v36
	v_mul_f32_e64 v1, v1, -v6
	v_cmp_gt_i32_e32 vcc, v0, v33
	v_cvt_pk_bf16_f32 v1, v1, s0
	v_mul_f32_e32 v2, v10, v2
	v_cndmask_b32_e32 v1, 0, v1, vcc
	ds_write_b16 v34, v1 offset:45088
	v_mul_f32_e64 v1, v2, -v22
	v_cmp_lt_i32_e32 vcc, v0, v33
	v_cvt_pk_bf16_f32 v1, v1, s0
	v_sub_u32_e32 v0, 63, v0
	v_cndmask_b32_e32 v2, 0, v1, vcc
	v_mad_u64_u32 v[0:1], s[0:1], v0, s42, v[32:33]
	v_sub_f32_e32 v1, v3, v30
	v_mul_f32_e32 v1, 0x3fb8aa3b, v1
	v_exp_f32_e32 v1, v1
	ds_write_b16 v0, v2 offset:51712
	v_sub_f32_e32 v2, v19, v31
	v_mul_f32_e32 v2, 0x3fb8aa3b, v2
	v_exp_f32_e32 v2, v2
	v_mul_f32_e32 v1, v11, v1
	v_or_b32_e32 v0, 19, v36
	v_mul_f32_e64 v1, v1, -v7
	v_cmp_gt_i32_e32 vcc, v0, v33
	v_cvt_pk_bf16_f32 v1, v1, s0
	ds_read_b128 v[4:7], v37 offset:61536
	v_mul_f32_e32 v2, v11, v2
	v_cndmask_b32_e32 v1, 0, v1, vcc
	ds_write_b16 v34, v1 offset:45232
	v_mul_f32_e64 v1, v2, -v23
	v_cmp_lt_i32_e32 vcc, v0, v33
	v_cvt_pk_bf16_f32 v1, v1, s0
	v_sub_u32_e32 v0, 63, v0
	v_cndmask_b32_e32 v2, 0, v1, vcc
	v_mad_u64_u32 v[0:1], s[0:1], v0, s42, v[32:33]
	ds_write_b16 v0, v2 offset:51712
	s_waitcnt lgkmcnt(2)
	v_sub_f32_e32 v0, v4, v30
	v_mul_f32_e32 v0, 0x3fb8aa3b, v0
	v_exp_f32_e32 v0, v0
	v_or_b32_e32 v20, 24, v36
	v_cmp_gt_i32_e32 vcc, v20, v33
	v_mul_f32_e32 v4, v12, v0
	ds_read_b128 v[0:3], v37 offset:61024
	ds_read_b128 v[8:11], v37 offset:61792
	ds_read_b128 v[16:19], v37 offset:61280
	s_waitcnt lgkmcnt(2)
	v_mul_f32_e64 v0, v4, -v0
	s_waitcnt lgkmcnt(1)
	v_sub_f32_e32 v8, v8, v31
	v_mul_f32_e32 v8, 0x3fb8aa3b, v8
	v_exp_f32_e32 v8, v8
	v_cvt_pk_bf16_f32 v0, v0, s0
	v_cndmask_b32_e32 v0, 0, v0, vcc
	ds_write_b16 v34, v0 offset:45952
	v_mul_f32_e32 v8, v12, v8
	s_waitcnt lgkmcnt(1)
	v_mul_f32_e64 v0, v8, -v16
	v_sub_u32_e32 v4, 63, v20
	v_cmp_lt_i32_e32 vcc, v20, v33
	v_cvt_pk_bf16_f32 v0, v0, s0
	v_mad_u64_u32 v[20:21], s[0:1], v4, s42, v[32:33]
	v_sub_f32_e32 v4, v5, v30
	v_mul_f32_e32 v4, 0x3fb8aa3b, v4
	v_exp_f32_e32 v4, v4
	v_sub_f32_e32 v5, v9, v31
	v_mul_f32_e32 v5, 0x3fb8aa3b, v5
	v_exp_f32_e32 v5, v5
	v_cndmask_b32_e32 v0, 0, v0, vcc
	v_mul_f32_e32 v4, v13, v4
	ds_write_b16 v20, v0 offset:51712
	v_or_b32_e32 v0, 25, v36
	v_mul_f32_e64 v1, v4, -v1
	v_cmp_gt_i32_e32 vcc, v0, v33
	v_cvt_pk_bf16_f32 v1, v1, s0
	v_mul_f32_e32 v5, v13, v5
	v_cndmask_b32_e32 v1, 0, v1, vcc
	ds_write_b16 v34, v1 offset:46096
	v_mul_f32_e64 v1, v5, -v17
	v_cmp_lt_i32_e32 vcc, v0, v33
	v_cvt_pk_bf16_f32 v1, v1, s0
	v_sub_u32_e32 v0, 63, v0
	v_cndmask_b32_e32 v4, 0, v1, vcc
	v_mad_u64_u32 v[0:1], s[0:1], v0, s42, v[32:33]
	v_sub_f32_e32 v1, v6, v30
	v_mul_f32_e32 v1, 0x3fb8aa3b, v1
	v_exp_f32_e32 v1, v1
	ds_write_b16 v0, v4 offset:51712
	v_sub_f32_e32 v4, v10, v31
	v_mul_f32_e32 v4, 0x3fb8aa3b, v4
	v_exp_f32_e32 v4, v4
	v_mul_f32_e32 v1, v14, v1
	v_or_b32_e32 v0, 26, v36
	v_mul_f32_e64 v1, v1, -v2
	v_cmp_gt_i32_e32 vcc, v0, v33
	v_cvt_pk_bf16_f32 v1, v1, s0
	v_mul_f32_e32 v4, v14, v4
	v_cndmask_b32_e32 v1, 0, v1, vcc
	ds_write_b16 v34, v1 offset:46240
	v_mul_f32_e64 v1, v4, -v18
	v_cmp_lt_i32_e32 vcc, v0, v33
	v_cvt_pk_bf16_f32 v1, v1, s0
	v_sub_u32_e32 v0, 63, v0
	v_cndmask_b32_e32 v2, 0, v1, vcc
	v_mad_u64_u32 v[0:1], s[0:1], v0, s42, v[32:33]
	v_sub_f32_e32 v1, v7, v30
	v_mul_f32_e32 v1, 0x3fb8aa3b, v1
	v_exp_f32_e32 v1, v1
	ds_write_b16 v0, v2 offset:51712
	v_sub_f32_e32 v2, v11, v31
	v_mul_f32_e32 v2, 0x3fb8aa3b, v2
	v_exp_f32_e32 v2, v2
	v_mul_f32_e32 v1, v15, v1
	v_or_b32_e32 v0, 27, v36
	v_mul_f32_e64 v1, v1, -v3
	v_cmp_gt_i32_e32 vcc, v0, v33
	v_cvt_pk_bf16_f32 v1, v1, s0
	v_mul_f32_e32 v2, v15, v2
	v_cndmask_b32_e32 v1, 0, v1, vcc
	ds_write_b16 v34, v1 offset:46384
	v_mul_f32_e64 v1, v2, -v19
	v_cmp_lt_i32_e32 vcc, v0, v33
	v_cvt_pk_bf16_f32 v1, v1, s0
	v_sub_u32_e32 v0, 63, v0
	v_cndmask_b32_e32 v2, 0, v1, vcc
	v_mad_u64_u32 v[0:1], s[0:1], v0, s42, v[32:33]
	ds_write_b16 v0, v2 offset:51712
	v_lshlrev_b32_e32 v2, 6, v29
	v_cmp_gt_i32_e32 vcc, 2, v29
	v_cmp_lt_i32_e64 s[0:1], 1, v29
	v_lshl_or_b32 v1, v154, 1, v2
	v_lshlrev_b32_e32 v0, 2, v41
	s_waitcnt lgkmcnt(0)
	s_barrier
	s_and_saveexec_b64 s[2:3], s[0:1]
	s_xor_b64 s[2:3], exec, s[2:3]
	s_cbranch_execz .LBB0_523
	v_xor_b32_e32 v7, 4, v41
	s_movk_i32 s4, 0x240
	ds_read2st64_b32 v[4:5], v0 offset0:238 offset1:240
	v_lshlrev_b32_e32 v7, 2, v7
	v_mad_u32_u24 v3, v185, s4, v1
	v_mad_u32_u24 v6, v157, s42, v1
	v_add_u32_e32 v7, 0xec, v7
	ds_read_u16 v9, v6 offset:33152
	ds_read2st64_b32 v[6:7], v7 offset0:239 offset1:241
	ds_read_u16 v3, v3 offset:33152
	s_waitcnt lgkmcnt(3)
	v_mul_f32_e32 v5, 0x3fb8aa3b, v5
	v_exp_f32_e32 v8, v5
	s_waitcnt lgkmcnt(2)
	v_lshlrev_b32_e32 v11, 16, v9
	s_waitcnt lgkmcnt(1)
	v_mul_f32_e32 v5, 0x3fb8aa3b, v7
	v_exp_f32_e32 v9, v5
	s_waitcnt lgkmcnt(0)
	v_lshlrev_b32_e32 v10, 16, v3
	v_mov_b32_e32 v5, v6
	v_pk_mul_f32 v[4:5], v[4:5], v[10:11]
	s_nop 0
	v_pk_mul_f32 v[72:73], v[4:5], v[8:9]

.LBB0_870:
	s_mov_b32 s8, 0x2aaaaaab
	v_mul_hi_i32 v0, v69, s8
	v_lshrrev_b32_e32 v1, 31, v0
	v_add_u32_e32 v102, v0, v1
	v_mov_b64_e32 v[0:1], s[48:49]
	v_mad_i64_i32 v[0:1], s[8:9], v102, s89, v[0:1]
	s_movk_i32 s8, 0xfe80
	s_nop 0
	v_mad_u64_u32 v[70:71], s[8:9], v102, s8, v[68:69]
	v_add_u32_e32 v2, 0xfffffd48, v70
	v_ashrrev_i32_e32 v3, 31, v2
	v_lshlrev_b64 v[64:65], 1, v[2:3]
	v_lshl_add_u64 v[4:5], v[0:1], 0, v[64:65]
	v_mov_b64_e32 v[0:1], s[70:71]
	v_mad_i64_i32 v[66:67], s[8:9], v102, s89, v[0:1]
	s_mov_b32 s8, 0x1980000
	s_nop 0
	v_add_co_u32_e32 v0, vcc, s8, v4
	v_lshl_add_u64 v[20:21], v[4:5], 0, s[20:21]
	s_nop 0
	v_addc_co_u32_e32 v1, vcc, 0, v5, vcc
	global_load_dwordx4 v[32:35], v[4:5], off offset:48
	global_load_dwordx4 v[40:43], v[4:5], off offset:32
	global_load_dwordx4 v[48:51], v[4:5], off offset:16
	global_load_dwordx4 v[56:59], v[4:5], off
	global_load_dwordx4 v[60:63], v[0:1], off
	global_load_dwordx4 v[36:39], v[20:21], off offset:48
	global_load_dwordx4 v[44:47], v[20:21], off offset:32
	global_load_dwordx4 v[52:55], v[20:21], off offset:16
	s_nop 0
	global_load_dwordx4 v[0:3], v[4:5], off offset:96
	global_load_dwordx4 v[8:11], v[4:5], off offset:80
	global_load_dwordx4 v[24:27], v[4:5], off offset:64
	global_load_dwordx4 v[16:19], v[4:5], off offset:112
	s_nop 0
	global_load_dwordx4 v[4:7], v[20:21], off offset:96
	global_load_dwordx4 v[12:15], v[20:21], off offset:80
	global_load_dwordx4 v[28:31], v[20:21], off offset:64
	s_nop 0
	global_load_dwordx4 v[20:23], v[20:21], off offset:112
	s_waitcnt vmcnt(19)
	v_lshl_add_u64 v[80:81], v[66:67], 0, v[64:65]
	global_load_dwordx4 v[64:67], v[80:81], off
	v_subrev_u32_e32 v71, 56, v70
	v_lshrrev_b32_e32 v176, 4, v71
	v_lshlrev_b32_e32 v71, 4, v102
	v_add_u32_e32 v69, s38, v69
	v_add_u32_e32 v68, s3, v68
	s_waitcnt vmcnt(11)
	v_lshlrev_b32_e32 v118, 16, v39
	s_waitcnt vmcnt(10)
	v_lshlrev_b32_e32 v116, 16, v47
	v_and_b32_e32 v117, 0xffff0000, v47
	s_waitcnt vmcnt(8)
	v_lshlrev_b32_e32 v73, 16, v3
	v_lshlrev_b32_e32 v72, 16, v2
	v_and_b32_e32 v3, 0xffff0000, v3
	v_and_b32_e32 v2, 0xffff0000, v2
	s_waitcnt vmcnt(4)
	v_lshlrev_b32_e32 v75, 16, v7
	v_lshlrev_b32_e32 v74, 16, v6
	v_and_b32_e32 v7, 0xffff0000, v7
	v_and_b32_e32 v6, 0xffff0000, v6
	v_pk_add_f32 v[82:83], v[72:73], v[74:75]
	v_pk_add_f32 v[84:85], v[2:3], v[6:7]
	v_lshlrev_b32_e32 v7, 16, v17
	v_lshlrev_b32_e32 v6, 16, v16
	s_waitcnt vmcnt(1)
	v_lshlrev_b32_e32 v73, 16, v21
	v_lshlrev_b32_e32 v72, 16, v20
	v_pk_add_f32 v[76:77], v[6:7], v[72:73]
	v_and_b32_e32 v7, 0xffff0000, v17
	v_and_b32_e32 v6, 0xffff0000, v16
	v_and_b32_e32 v17, 0xffff0000, v21
	v_and_b32_e32 v16, 0xffff0000, v20
	v_pk_add_f32 v[78:79], v[6:7], v[16:17]
	v_lshlrev_b32_e32 v17, 16, v23
	v_pk_mul_f32 v[6:7], v[78:79], v[78:79]
	v_lshlrev_b32_e32 v16, 16, v22
	v_pk_fma_f32 v[86:87], v[76:77], v[76:77], v[6:7]
	v_lshlrev_b32_e32 v7, 16, v19
	v_lshlrev_b32_e32 v6, 16, v18
	v_pk_add_f32 v[72:73], v[6:7], v[16:17]
	v_and_b32_e32 v7, 0xffff0000, v19
	v_and_b32_e32 v6, 0xffff0000, v18
	v_and_b32_e32 v17, 0xffff0000, v23
	v_and_b32_e32 v16, 0xffff0000, v22
	v_pk_add_f32 v[74:75], v[6:7], v[16:17]
	v_lshlrev_b32_e32 v16, 16, v59
	v_and_b32_e32 v17, 0xffff0000, v59
	v_lshlrev_b32_e32 v18, 16, v63
	v_and_b32_e32 v19, 0xffff0000, v63
	v_pk_add_f32 v[88:89], v[16:17], v[18:19]
	v_lshlrev_b32_e32 v16, 16, v58
	v_and_b32_e32 v17, 0xffff0000, v58
	v_lshlrev_b32_e32 v18, 16, v62
	v_and_b32_e32 v19, 0xffff0000, v62
	s_waitcnt vmcnt(0)
	v_lshlrev_b32_e32 v96, 16, v66
	v_and_b32_e32 v66, 0xffff0000, v66
	v_pk_add_f32 v[58:59], v[16:17], v[18:19]
	v_mul_f32_e32 v16, 0xbfb8aa3b, v96
	v_mul_f32_e32 v95, 0xbfb8aa3b, v66
	v_exp_f32_e32 v94, v16
	v_exp_f32_e32 v95, v95
	global_load_dwordx4 v[16:19], v177, s[4:5] offset:16
	global_load_dwordx4 v[20:23], v177, s[4:5]
	v_pk_mul_f32 v[6:7], v[74:75], v[74:75]
	v_lshlrev_b32_e32 v112, 16, v48
	v_pk_add_f32 v[94:95], v[94:95], 1.0 op_sel_hi:[1,0]
	v_pk_fma_f32 v[90:91], v[72:73], v[72:73], v[6:7]
	v_ashrrev_i32_e32 v6, 5, v102
	v_ashrrev_i32_e32 v7, 31, v6
	v_lshlrev_b64 v[6:7], 16, v[6:7]
	v_rcp_f32_e32 v97, v95
	s_nop 0
	v_mul_f32_e32 v95, v66, v97
	v_lshl_add_u64 v[6:7], s[64:65], 0, v[6:7]
	v_and_b32_e32 v113, 0xffff0000, v48
	v_lshlrev_b32_e32 v48, 16, v52
	v_rcp_f32_e32 v66, v94
	s_nop 0
	v_mul_f32_e32 v94, v96, v66
	v_lshlrev_b32_e32 v96, 16, v57
	v_and_b32_e32 v97, 0xffff0000, v57
	v_lshlrev_b32_e32 v57, 16, v65
	v_lshlrev_b32_e32 v98, 16, v61
	v_and_b32_e32 v99, 0xffff0000, v61
	v_and_b32_e32 v61, 0xffff0000, v65
	v_mul_f32_e32 v65, 0xbfb8aa3b, v57
	v_pk_add_f32 v[96:97], v[96:97], v[98:99]
	v_exp_f32_e32 v98, v65
	v_mul_f32_e32 v65, 0xbfb8aa3b, v61
	v_exp_f32_e32 v99, v65
	v_and_b32_e32 v47, 0xffff0000, v41
	v_and_b32_e32 v119, 0xffff0000, v39
	v_and_b32_e32 v39, 0xffff0000, v33
	v_pk_add_f32 v[98:99], v[98:99], 1.0 op_sel_hi:[1,0]
	v_pk_mul_f32 v[92:93], v[88:89], v[88:89]
	v_pk_mul_f32 v[100:101], v[96:97], v[96:97]
	v_lshlrev_b32_e32 v120, 16, v31
	v_and_b32_e32 v121, 0xffff0000, v31
	v_rcp_f32_e32 v65, v99
	s_nop 0
	v_mul_f32_e32 v99, v61, v65
	v_and_b32_e32 v105, 0xffff0000, v56
	v_pk_mul_f32 v[62:63], v[58:59], v[58:59]
	v_lshlrev_b32_e32 v110, 16, v53
	v_rcp_f32_e32 v61, v98
	s_nop 0
	v_mul_f32_e32 v98, v57, v61
	v_lshlrev_b32_e32 v104, 16, v56
	v_lshlrev_b32_e32 v56, 16, v60
	v_and_b32_e32 v57, 0xffff0000, v60
	v_lshlrev_b32_e32 v66, 16, v64
	v_and_b32_e32 v64, 0xffff0000, v64
	v_pk_add_f32 v[60:61], v[104:105], v[56:57]
	v_mul_f32_e32 v56, 0xbfb8aa3b, v66
	v_mul_f32_e32 v57, 0xbfb8aa3b, v64
	v_exp_f32_e32 v56, v56
	v_exp_f32_e32 v57, v57
	v_pk_mul_f32 v[104:105], v[60:61], v[60:61]
	v_and_b32_e32 v111, 0xffff0000, v53
	v_and_b32_e32 v31, 0xffff0000, v25
	v_pk_add_f32 v[56:57], v[56:57], 1.0 op_sel_hi:[1,0]
	v_add_f32_e32 v62, v62, v63
	v_lshlrev_b32_e32 v122, 16, v15
	v_and_b32_e32 v123, 0xffff0000, v15
	v_lshlrev_b32_e32 v154, 16, v5
	v_rcp_f32_e32 v65, v57
	s_nop 0
	v_mul_f32_e32 v65, v64, v65
	v_and_b32_e32 v155, 0xffff0000, v5
	v_pk_mul_f32 v[2:3], v[84:85], v[84:85]
	v_rcp_f32_e32 v57, v56
	s_nop 0
	v_mul_f32_e32 v64, v66, v57
	v_lshlrev_b32_e32 v66, 16, v67
	v_and_b32_e32 v67, 0xffff0000, v67
	v_mul_f32_e32 v56, 0xbfb8aa3b, v66
	v_mul_f32_e32 v57, 0xbfb8aa3b, v67
	v_exp_f32_e32 v56, v56
	v_exp_f32_e32 v57, v57
	v_pk_fma_f32 v[2:3], v[82:83], v[82:83], v[2:3]
	v_pk_add_f32 v[56:57], v[56:57], 1.0 op_sel_hi:[1,0]
	s_nop 0
	s_nop 0
	v_rcp_f32_e32 v103, v57
	s_nop 0
	v_mul_f32_e32 v67, v67, v103
	v_and_b32_e32 v109, 0xffff0000, v50
	v_rcp_f32_e32 v57, v56
	s_nop 0
	v_mul_f32_e32 v66, v66, v57
	v_lshlrev_b64 v[56:57], 10, v[176:177]
	v_lshl_add_u64 v[56:57], v[6:7], 0, v[56:57]
	v_and_b32_e32 v176, 0x1f0, v71
	v_lshl_add_u64 v[102:103], v[56:57], 0, v[176:177]
	v_lshlrev_b32_e32 v56, 16, v51
	v_and_b32_e32 v57, 0xffff0000, v51
	v_lshlrev_b32_e32 v106, 16, v55
	v_and_b32_e32 v107, 0xffff0000, v55
	v_lshlrev_b32_e32 v108, 16, v50
	v_lshlrev_b32_e32 v50, 16, v54
	v_and_b32_e32 v51, 0xffff0000, v54
	v_lshlrev_b32_e32 v54, 16, v49
	v_and_b32_e32 v55, 0xffff0000, v49
	v_and_b32_e32 v49, 0xffff0000, v52
	v_subrev_u32_e32 v71, 48, v70
	v_pk_add_f32 v[48:49], v[112:113], v[48:49]
	v_lshrrev_b32_e32 v112, 4, v71
	v_mov_b32_e32 v113, v177
	v_lshlrev_b64 v[112:113], 10, v[112:113]
	v_lshl_add_u64 v[112:113], v[6:7], 0, v[112:113]
	v_lshl_add_u64 v[114:115], v[112:113], 0, v[176:177]
	v_lshlrev_b32_e32 v112, 16, v43
	v_and_b32_e32 v113, 0xffff0000, v43
	v_pk_add_f32 v[112:113], v[112:113], v[116:117]
	v_lshlrev_b32_e32 v116, 16, v42
	v_and_b32_e32 v117, 0xffff0000, v42
	v_lshlrev_b32_e32 v42, 16, v46
	v_and_b32_e32 v43, 0xffff0000, v46
	v_pk_add_f32 v[42:43], v[116:117], v[42:43]
	v_lshlrev_b32_e32 v46, 16, v41
	v_lshlrev_b32_e32 v116, 16, v45
	v_and_b32_e32 v117, 0xffff0000, v45
	v_pk_add_f32 v[46:47], v[46:47], v[116:117]
	v_lshlrev_b32_e32 v116, 16, v40
	v_and_b32_e32 v117, 0xffff0000, v40
	v_lshlrev_b32_e32 v40, 16, v44
	v_and_b32_e32 v41, 0xffff0000, v44
	v_pk_add_f32 v[44:45], v[116:117], v[40:41]
	v_subrev_u32_e32 v40, 40, v70
	v_lshrrev_b32_e32 v40, 4, v40
	v_mov_b32_e32 v41, v177
	v_lshlrev_b64 v[40:41], 10, v[40:41]
	v_lshl_add_u64 v[40:41], v[6:7], 0, v[40:41]
	v_lshl_add_u64 v[116:117], v[40:41], 0, v[176:177]
	v_lshlrev_b32_e32 v40, 16, v35
	v_and_b32_e32 v41, 0xffff0000, v35
	v_pk_add_f32 v[40:41], v[40:41], v[118:119]
	v_lshlrev_b32_e32 v118, 16, v34
	v_and_b32_e32 v119, 0xffff0000, v34
	v_lshlrev_b32_e32 v34, 16, v38
	v_and_b32_e32 v35, 0xffff0000, v38
	v_pk_add_f32 v[34:35], v[118:119], v[34:35]
	v_lshlrev_b32_e32 v38, 16, v33
	v_lshlrev_b32_e32 v118, 16, v37
	v_and_b32_e32 v119, 0xffff0000, v37
	v_pk_add_f32 v[38:39], v[38:39], v[118:119]
	v_lshlrev_b32_e32 v118, 16, v32
	v_and_b32_e32 v119, 0xffff0000, v32
	v_lshlrev_b32_e32 v32, 16, v36
	v_and_b32_e32 v33, 0xffff0000, v36
	v_pk_add_f32 v[36:37], v[118:119], v[32:33]
	v_subrev_u32_e32 v32, 32, v70
	v_lshrrev_b32_e32 v32, 4, v32
	v_mov_b32_e32 v33, v177
	v_lshlrev_b64 v[32:33], 10, v[32:33]
	v_lshl_add_u64 v[32:33], v[6:7], 0, v[32:33]
	v_lshl_add_u64 v[118:119], v[32:33], 0, v[176:177]
	v_lshlrev_b32_e32 v32, 16, v27
	v_and_b32_e32 v33, 0xffff0000, v27
	v_pk_add_f32 v[32:33], v[32:33], v[120:121]
	v_lshlrev_b32_e32 v120, 16, v26
	v_and_b32_e32 v121, 0xffff0000, v26
	v_lshlrev_b32_e32 v26, 16, v30
	v_and_b32_e32 v27, 0xffff0000, v30
	v_add_f32_e32 v71, v92, v93
	v_add_f32_e32 v92, v100, v101
	v_add_f32_e32 v93, v104, v105
	v_pk_add_f32 v[26:27], v[120:121], v[26:27]
	v_lshlrev_b32_e32 v30, 16, v25
	v_lshlrev_b32_e32 v120, 16, v29
	v_and_b32_e32 v121, 0xffff0000, v29
	v_add_f32_e32 v92, v93, v92
	v_pk_add_f32 v[54:55], v[54:55], v[110:111]
	v_pk_mul_f32 v[52:53], v[48:49], v[48:49]
	v_pk_add_f32 v[30:31], v[30:31], v[120:121]
	v_lshlrev_b32_e32 v120, 16, v24
	v_and_b32_e32 v121, 0xffff0000, v24
	v_lshlrev_b32_e32 v24, 16, v28
	v_and_b32_e32 v25, 0xffff0000, v28
	v_add_f32_e32 v62, v62, v92
	v_pk_add_f32 v[50:51], v[108:109], v[50:51]
	v_pk_mul_f32 v[110:111], v[54:55], v[54:55]
	v_pk_add_f32 v[28:29], v[120:121], v[24:25]
	v_subrev_u32_e32 v24, 24, v70
	v_add_f32_e32 v62, v71, v62
	v_add_f32_e32 v52, v52, v53
	v_pk_add_f32 v[56:57], v[56:57], v[106:107]
	v_pk_mul_f32 v[108:109], v[50:51], v[50:51]
	v_lshrrev_b32_e32 v24, 4, v24
	v_mov_b32_e32 v25, v177
	v_add_f32_e32 v52, v52, v62
	v_add_f32_e32 v53, v110, v111
	v_pk_mul_f32 v[106:107], v[56:57], v[56:57]
	v_lshlrev_b64 v[24:25], 10, v[24:25]
	v_add_f32_e32 v52, v53, v52
	v_add_f32_e32 v53, v108, v109
	v_pk_mul_f32 v[130:131], v[44:45], v[44:45]
	v_lshl_add_u64 v[24:25], v[6:7], 0, v[24:25]
	v_add_f32_e32 v52, v53, v52
	v_add_f32_e32 v53, v106, v107
	v_pk_mul_f32 v[128:129], v[46:47], v[46:47]
	v_lshl_add_u64 v[120:121], v[24:25], 0, v[176:177]
	v_lshlrev_b32_e32 v24, 16, v11
	v_and_b32_e32 v25, 0xffff0000, v11
	v_add_f32_e32 v52, v53, v52
	v_add_f32_e32 v53, v130, v131
	v_pk_mul_f32 v[126:127], v[42:43], v[42:43]
	v_pk_add_f32 v[24:25], v[24:25], v[122:123]
	v_lshlrev_b32_e32 v122, 16, v10
	v_and_b32_e32 v123, 0xffff0000, v10
	v_lshlrev_b32_e32 v10, 16, v14
	v_and_b32_e32 v11, 0xffff0000, v14
	v_add_f32_e32 v52, v53, v52
	v_add_f32_e32 v53, v128, v129
	v_pk_mul_f32 v[124:125], v[112:113], v[112:113]
	v_pk_add_f32 v[10:11], v[122:123], v[10:11]
	v_add_f32_e32 v52, v53, v52
	v_add_f32_e32 v53, v126, v127
	v_pk_mul_f32 v[138:139], v[36:37], v[36:37]
	v_mov_b32_e32 v122, v25
	v_mov_b32_e32 v123, v11
	v_add_f32_e32 v52, v53, v52
	v_add_f32_e32 v53, v124, v125
	v_pk_mul_f32 v[136:137], v[38:39], v[38:39]
	v_mov_b32_e32 v14, v24
	v_mov_b32_e32 v15, v10
	v_pk_mul_f32 v[122:123], v[122:123], v[122:123]
	v_add_f32_e32 v52, v53, v52
	v_add_f32_e32 v53, v138, v139
	v_pk_mul_f32 v[134:135], v[34:35], v[34:35]
	v_pk_fma_f32 v[148:149], v[14:15], v[14:15], v[122:123]
	v_lshlrev_b32_e32 v14, 16, v9
	v_and_b32_e32 v15, 0xffff0000, v9
	v_lshlrev_b32_e32 v122, 16, v13
	v_and_b32_e32 v123, 0xffff0000, v13
	v_add_f32_e32 v52, v53, v52
	v_add_f32_e32 v53, v136, v137
	v_pk_mul_f32 v[132:133], v[40:41], v[40:41]
	v_pk_add_f32 v[14:15], v[14:15], v[122:123]
	v_lshlrev_b32_e32 v122, 16, v8
	v_and_b32_e32 v123, 0xffff0000, v8
	v_lshlrev_b32_e32 v8, 16, v12
	v_and_b32_e32 v9, 0xffff0000, v12
	v_add_f32_e32 v52, v53, v52
	v_add_f32_e32 v53, v134, v135
	v_pk_mul_f32 v[146:147], v[28:29], v[28:29]
	v_pk_add_f32 v[12:13], v[122:123], v[8:9]
	v_add_u32_e32 v8, -16, v70
	v_add_f32_e32 v52, v53, v52
	v_add_f32_e32 v53, v132, v133
	v_pk_mul_f32 v[144:145], v[30:31], v[30:31]
	v_lshrrev_b32_e32 v8, 4, v8
	v_mov_b32_e32 v9, v177
	v_add_f32_e32 v52, v53, v52
	v_add_f32_e32 v53, v146, v147
	v_pk_mul_f32 v[142:143], v[26:27], v[26:27]
	v_lshlrev_b64 v[8:9], 10, v[8:9]
	v_add_f32_e32 v52, v53, v52
	v_add_f32_e32 v53, v144, v145
	v_pk_mul_f32 v[140:141], v[32:33], v[32:33]
	v_lshl_add_u64 v[8:9], v[6:7], 0, v[8:9]
	v_add_f32_e32 v52, v53, v52
	v_add_f32_e32 v53, v142, v143
	v_pk_mul_f32 v[152:153], v[12:13], v[12:13]
	v_lshl_add_u64 v[122:123], v[8:9], 0, v[176:177]
	v_lshlrev_b32_e32 v8, 16, v1
	v_and_b32_e32 v9, 0xffff0000, v1
	v_add_f32_e32 v52, v53, v52
	v_add_f32_e32 v53, v140, v141
	v_pk_mul_f32 v[150:151], v[14:15], v[14:15]
	v_pk_add_f32 v[8:9], v[8:9], v[154:155]
	v_lshlrev_b32_e32 v154, 16, v0
	v_and_b32_e32 v155, 0xffff0000, v0
	v_lshlrev_b32_e32 v0, 16, v4
	v_and_b32_e32 v1, 0xffff0000, v4
	v_add_f32_e32 v52, v53, v52
	v_add_f32_e32 v53, v152, v153
	v_pk_add_f32 v[0:1], v[154:155], v[0:1]
	v_add_f32_e32 v52, v53, v52
	v_add_f32_e32 v53, v150, v151
	v_mov_b32_e32 v154, v9
	v_mov_b32_e32 v155, v1
	v_add_f32_e32 v52, v53, v52
	v_mov_b32_e32 v4, v8
	v_mov_b32_e32 v5, v0
	v_pk_mul_f32 v[154:155], v[154:155], v[154:155]
	v_add_f32_e32 v52, v149, v52
	v_pk_fma_f32 v[4:5], v[4:5], v[4:5], v[154:155]
	v_add_f32_e32 v52, v148, v52
	v_add_f32_e32 v5, v5, v52
	v_add_f32_e32 v4, v4, v5
	v_add_f32_e32 v2, v2, v4
	v_add_f32_e32 v2, v3, v2
	v_add_f32_e32 v2, v86, v2
	v_add_f32_e32 v2, v87, v2
	v_add_f32_e32 v2, v90, v2
	v_add_f32_e32 v2, v91, v2
	v_fmamk_f32 v2, v2, 0x3c800000, v178
	v_cmp_gt_f32_e32 vcc, s40, v2
	v_mul_f32_e32 v3, 0x4b800000, v2
	s_nop 0
	v_cndmask_b32_e32 v2, v2, v3, vcc
	v_rsq_f32_e32 v2, v2
	s_nop 0
	v_mul_f32_e32 v3, 0x45800000, v2
	v_cndmask_b32_e32 v4, v2, v3, vcc
	v_pk_mul_f32 v[2:3], v[60:61], v[4:5] op_sel_hi:[1,0]
	s_waitcnt vmcnt(0)
	v_pk_mul_f32 v[2:3], v[20:21], v[2:3]
	s_nop 0
	v_pk_mul_f32 v[2:3], v[64:65], v[2:3]
	s_nop 0
	v_cvt_pk_bf16_f32 v20, v2, v3
	v_pk_mul_f32 v[2:3], v[96:97], v[4:5] op_sel_hi:[1,0]
	s_nop 0
	v_pk_mul_f32 v[2:3], v[22:23], v[2:3]
	s_nop 0
	v_pk_mul_f32 v[2:3], v[98:99], v[2:3]
	s_nop 0
	v_cvt_pk_bf16_f32 v21, v2, v3
	v_pk_mul_f32 v[2:3], v[58:59], v[4:5] op_sel_hi:[1,0]
	s_nop 0
	v_pk_mul_f32 v[2:3], v[16:17], v[2:3]
	s_nop 0
	v_pk_mul_f32 v[2:3], v[94:95], v[2:3]
	s_nop 0
	v_cvt_pk_bf16_f32 v22, v2, v3
	v_pk_mul_f32 v[2:3], v[88:89], v[4:5] op_sel_hi:[1,0]
	s_nop 0
	v_pk_mul_f32 v[2:3], v[18:19], v[2:3]
	s_nop 0
	v_pk_mul_f32 v[2:3], v[66:67], v[2:3]
	s_nop 0
	v_cvt_pk_bf16_f32 v23, v2, v3
	global_store_dwordx4 v[102:103], v[20:23], off
	global_load_dwordx4 v[16:19], v[80:81], off offset:16
	s_nop 0
	global_load_dwordx4 v[20:23], v177, s[4:5] offset:48
	global_load_dwordx4 v[58:61], v177, s[4:5] offset:32
	s_waitcnt vmcnt(2)
	v_lshlrev_b32_e32 v5, 16, v16
	v_and_b32_e32 v16, 0xffff0000, v16
	v_mul_f32_e32 v2, 0xbfb8aa3b, v5
	v_mul_f32_e32 v3, 0xbfb8aa3b, v16
	v_exp_f32_e32 v2, v2
	v_exp_f32_e32 v3, v3
	v_pk_mul_f32 v[48:49], v[48:49], v[4:5] op_sel_hi:[1,0]
	v_pk_add_f32 v[2:3], v[2:3], 1.0 op_sel_hi:[1,0]
	s_nop 0
	s_waitcnt vmcnt(0)
	v_pk_mul_f32 v[48:49], v[58:59], v[48:49]
	v_rcp_f32_e32 v52, v3
	s_nop 0
	v_mul_f32_e32 v3, v16, v52
	s_nop 0
	v_rcp_f32_e32 v16, v2
	s_nop 0
	v_mul_f32_e32 v2, v5, v16
	v_pk_mul_f32 v[2:3], v[2:3], v[48:49]
	v_lshlrev_b32_e32 v5, 16, v17
	v_and_b32_e32 v17, 0xffff0000, v17
	v_cvt_pk_bf16_f32 v16, v2, v3
	v_mul_f32_e32 v2, 0xbfb8aa3b, v5
	v_mul_f32_e32 v3, 0xbfb8aa3b, v17
	v_exp_f32_e32 v2, v2
	v_exp_f32_e32 v3, v3
	v_pk_mul_f32 v[48:49], v[54:55], v[4:5] op_sel_hi:[1,0]
	v_pk_add_f32 v[2:3], v[2:3], 1.0 op_sel_hi:[1,0]
	s_nop 0
	v_pk_mul_f32 v[48:49], v[60:61], v[48:49]
	v_rcp_f32_e32 v52, v3
	s_nop 0
	v_mul_f32_e32 v3, v17, v52
	s_nop 0
	v_rcp_f32_e32 v17, v2
	s_nop 0
	v_mul_f32_e32 v2, v5, v17
	v_pk_mul_f32 v[2:3], v[2:3], v[48:49]
	v_lshlrev_b32_e32 v5, 16, v18
	v_and_b32_e32 v18, 0xffff0000, v18
	v_cvt_pk_bf16_f32 v17, v2, v3
	v_mul_f32_e32 v2, 0xbfb8aa3b, v5
	v_mul_f32_e32 v3, 0xbfb8aa3b, v18
	v_exp_f32_e32 v2, v2
	v_exp_f32_e32 v3, v3
	v_pk_mul_f32 v[48:49], v[50:51], v[4:5] op_sel_hi:[1,0]
	v_pk_add_f32 v[2:3], v[2:3], 1.0 op_sel_hi:[1,0]
	v_pk_mul_f32 v[20:21], v[20:21], v[48:49]
	s_nop 0
	v_rcp_f32_e32 v48, v3
	s_nop 0
	v_mul_f32_e32 v3, v18, v48
	s_nop 0
	v_rcp_f32_e32 v18, v2
	s_nop 0
	v_mul_f32_e32 v2, v5, v18
	v_pk_mul_f32 v[2:3], v[2:3], v[20:21]
	v_lshlrev_b32_e32 v5, 16, v19
	v_and_b32_e32 v19, 0xffff0000, v19
	v_cvt_pk_bf16_f32 v18, v2, v3
	v_mul_f32_e32 v2, 0xbfb8aa3b, v5
	v_mul_f32_e32 v3, 0xbfb8aa3b, v19
	v_exp_f32_e32 v2, v2
	v_exp_f32_e32 v3, v3
	v_pk_mul_f32 v[20:21], v[56:57], v[4:5] op_sel_hi:[1,0]
	v_pk_add_f32 v[2:3], v[2:3], 1.0 op_sel_hi:[1,0]
	v_pk_mul_f32 v[20:21], v[22:23], v[20:21]
	s_nop 0
	v_rcp_f32_e32 v22, v3
	s_nop 0
	v_mul_f32_e32 v3, v19, v22
	s_nop 0
	v_rcp_f32_e32 v19, v2
	s_nop 0
	v_mul_f32_e32 v2, v5, v19
	v_pk_mul_f32 v[2:3], v[2:3], v[20:21]
	s_nop 0
	v_cvt_pk_bf16_f32 v19, v2, v3
	global_store_dwordx4 v[114:115], v[16:19], off offset:512
	global_load_dwordx4 v[16:19], v[80:81], off offset:32
	s_nop 0
	global_load_dwordx4 v[20:23], v177, s[4:5] offset:80
	global_load_dwordx4 v[48:51], v177, s[4:5] offset:64
	s_waitcnt vmcnt(2)
	v_lshlrev_b32_e32 v5, 16, v16
	v_and_b32_e32 v16, 0xffff0000, v16
	v_mul_f32_e32 v2, 0xbfb8aa3b, v5
	v_mul_f32_e32 v3, 0xbfb8aa3b, v16
	v_exp_f32_e32 v2, v2
	v_exp_f32_e32 v3, v3
	v_pk_mul_f32 v[44:45], v[44:45], v[4:5] op_sel_hi:[1,0]
	v_pk_add_f32 v[2:3], v[2:3], 1.0 op_sel_hi:[1,0]
	s_waitcnt vmcnt(0)
	v_pk_mul_f32 v[44:45], v[48:49], v[44:45]
	s_nop 0
	v_rcp_f32_e32 v48, v3
	s_nop 0
	v_mul_f32_e32 v3, v16, v48
	s_nop 0
	v_rcp_f32_e32 v16, v2
	s_nop 0
	v_mul_f32_e32 v2, v5, v16
	v_pk_mul_f32 v[2:3], v[2:3], v[44:45]
	v_lshlrev_b32_e32 v5, 16, v17
	v_and_b32_e32 v17, 0xffff0000, v17
	v_cvt_pk_bf16_f32 v16, v2, v3
	v_mul_f32_e32 v2, 0xbfb8aa3b, v5
	v_mul_f32_e32 v3, 0xbfb8aa3b, v17
	v_exp_f32_e32 v2, v2
	v_exp_f32_e32 v3, v3
	v_pk_mul_f32 v[44:45], v[46:47], v[4:5] op_sel_hi:[1,0]
	v_pk_add_f32 v[2:3], v[2:3], 1.0 op_sel_hi:[1,0]
	s_nop 0
	v_pk_mul_f32 v[44:45], v[50:51], v[44:45]
	v_rcp_f32_e32 v46, v3
	s_nop 0
	v_mul_f32_e32 v3, v17, v46
	s_nop 0
	v_rcp_f32_e32 v17, v2
	s_nop 0
	v_mul_f32_e32 v2, v5, v17
	v_pk_mul_f32 v[2:3], v[2:3], v[44:45]
	v_lshlrev_b32_e32 v5, 16, v18
	v_and_b32_e32 v18, 0xffff0000, v18
	v_cvt_pk_bf16_f32 v17, v2, v3
	v_mul_f32_e32 v2, 0xbfb8aa3b, v5
	v_mul_f32_e32 v3, 0xbfb8aa3b, v18
	v_exp_f32_e32 v2, v2
	v_exp_f32_e32 v3, v3
	v_pk_mul_f32 v[42:43], v[42:43], v[4:5] op_sel_hi:[1,0]
	v_pk_add_f32 v[2:3], v[2:3], 1.0 op_sel_hi:[1,0]
	v_pk_mul_f32 v[20:21], v[20:21], v[42:43]
	s_nop 0
	v_rcp_f32_e32 v42, v3
	s_nop 0
	v_mul_f32_e32 v3, v18, v42
	s_nop 0
	v_rcp_f32_e32 v18, v2
	s_nop 0
	v_mul_f32_e32 v2, v5, v18
	v_pk_mul_f32 v[2:3], v[2:3], v[20:21]
	v_lshlrev_b32_e32 v5, 16, v19
	v_and_b32_e32 v19, 0xffff0000, v19
	v_cvt_pk_bf16_f32 v18, v2, v3
	v_mul_f32_e32 v2, 0xbfb8aa3b, v5
	v_mul_f32_e32 v3, 0xbfb8aa3b, v19
	v_exp_f32_e32 v2, v2
	v_exp_f32_e32 v3, v3
	v_pk_mul_f32 v[20:21], v[112:113], v[4:5] op_sel_hi:[1,0]
	v_pk_add_f32 v[2:3], v[2:3], 1.0 op_sel_hi:[1,0]
	v_pk_mul_f32 v[20:21], v[22:23], v[20:21]
	s_nop 0
	v_rcp_f32_e32 v22, v3
	s_nop 0
	v_mul_f32_e32 v3, v19, v22
	s_nop 0
	v_rcp_f32_e32 v19, v2
	s_nop 0
	v_mul_f32_e32 v2, v5, v19
	v_pk_mul_f32 v[2:3], v[2:3], v[20:21]
	s_nop 0
	v_cvt_pk_bf16_f32 v19, v2, v3
	global_store_dwordx4 v[116:117], v[16:19], off
	global_load_dwordx4 v[16:19], v[80:81], off offset:48
	s_nop 0
	global_load_dwordx4 v[20:23], v177, s[4:5] offset:112
	global_load_dwordx4 v[42:45], v177, s[4:5] offset:96
	s_waitcnt vmcnt(2)
	v_lshlrev_b32_e32 v5, 16, v16
	v_and_b32_e32 v16, 0xffff0000, v16
	v_mul_f32_e32 v2, 0xbfb8aa3b, v5
	v_mul_f32_e32 v3, 0xbfb8aa3b, v16
	v_exp_f32_e32 v2, v2
	v_exp_f32_e32 v3, v3
	v_pk_mul_f32 v[36:37], v[36:37], v[4:5] op_sel_hi:[1,0]
	v_pk_add_f32 v[2:3], v[2:3], 1.0 op_sel_hi:[1,0]
	s_waitcnt vmcnt(0)
	v_pk_mul_f32 v[36:37], v[36:37], v[42:43]
	s_nop 0
	v_rcp_f32_e32 v42, v3
	s_nop 0
	v_mul_f32_e32 v3, v16, v42
	s_nop 0
	v_rcp_f32_e32 v16, v2
	s_nop 0
	v_mul_f32_e32 v2, v5, v16
	v_pk_mul_f32 v[2:3], v[36:37], v[2:3]
	v_lshlrev_b32_e32 v5, 16, v17
	v_and_b32_e32 v17, 0xffff0000, v17
	v_cvt_pk_bf16_f32 v16, v2, v3
	v_mul_f32_e32 v2, 0xbfb8aa3b, v5
	v_mul_f32_e32 v3, 0xbfb8aa3b, v17
	v_exp_f32_e32 v2, v2
	v_exp_f32_e32 v3, v3
	v_pk_mul_f32 v[36:37], v[38:39], v[4:5] op_sel_hi:[1,0]
	v_pk_add_f32 v[2:3], v[2:3], 1.0 op_sel_hi:[1,0]
	s_nop 0
	v_pk_mul_f32 v[36:37], v[36:37], v[44:45]
	v_rcp_f32_e32 v38, v3
	s_nop 0
	v_mul_f32_e32 v3, v17, v38
	s_nop 0
	v_rcp_f32_e32 v17, v2
	s_nop 0
	v_mul_f32_e32 v2, v5, v17
	v_pk_mul_f32 v[2:3], v[36:37], v[2:3]
	v_lshlrev_b32_e32 v5, 16, v18
	v_and_b32_e32 v18, 0xffff0000, v18
	v_cvt_pk_bf16_f32 v17, v2, v3
	v_mul_f32_e32 v2, 0xbfb8aa3b, v5
	v_mul_f32_e32 v3, 0xbfb8aa3b, v18
	v_exp_f32_e32 v2, v2
	v_exp_f32_e32 v3, v3
	v_pk_mul_f32 v[34:35], v[34:35], v[4:5] op_sel_hi:[1,0]
	v_pk_add_f32 v[2:3], v[2:3], 1.0 op_sel_hi:[1,0]
	v_pk_mul_f32 v[20:21], v[34:35], v[20:21]
	s_nop 0
	v_rcp_f32_e32 v34, v3
	s_nop 0
	v_mul_f32_e32 v3, v18, v34
	s_nop 0
	v_rcp_f32_e32 v18, v2
	s_nop 0
	v_mul_f32_e32 v2, v5, v18
	v_pk_mul_f32 v[2:3], v[20:21], v[2:3]
	v_lshlrev_b32_e32 v5, 16, v19
	v_and_b32_e32 v19, 0xffff0000, v19
	v_cvt_pk_bf16_f32 v18, v2, v3
	v_mul_f32_e32 v2, 0xbfb8aa3b, v5
	v_mul_f32_e32 v3, 0xbfb8aa3b, v19
	v_exp_f32_e32 v2, v2
	v_exp_f32_e32 v3, v3
	v_pk_mul_f32 v[20:21], v[40:41], v[4:5] op_sel_hi:[1,0]
	v_pk_add_f32 v[2:3], v[2:3], 1.0 op_sel_hi:[1,0]
	v_pk_mul_f32 v[20:21], v[20:21], v[22:23]
	s_nop 0
	v_rcp_f32_e32 v22, v3
	s_nop 0
	v_mul_f32_e32 v3, v19, v22
	s_nop 0
	v_rcp_f32_e32 v19, v2
	s_nop 0
	v_mul_f32_e32 v2, v5, v19
	v_pk_mul_f32 v[2:3], v[2:3], v[20:21]
	s_nop 0
	v_cvt_pk_bf16_f32 v19, v2, v3
	global_store_dwordx4 v[118:119], v[16:19], off offset:512
	global_load_dwordx4 v[16:19], v[80:81], off offset:64
	s_nop 0
	global_load_dwordx4 v[20:23], v177, s[4:5] offset:144
	global_load_dwordx4 v[34:37], v177, s[4:5] offset:128
	s_waitcnt vmcnt(2)
	v_lshlrev_b32_e32 v5, 16, v16
	v_and_b32_e32 v16, 0xffff0000, v16
	v_mul_f32_e32 v2, 0xbfb8aa3b, v5
	v_mul_f32_e32 v3, 0xbfb8aa3b, v16
	v_exp_f32_e32 v2, v2
	v_exp_f32_e32 v3, v3
	v_pk_mul_f32 v[28:29], v[28:29], v[4:5] op_sel_hi:[1,0]
	v_pk_add_f32 v[2:3], v[2:3], 1.0 op_sel_hi:[1,0]
	s_waitcnt vmcnt(0)
	v_pk_mul_f32 v[28:29], v[28:29], v[34:35]
	s_nop 0
	v_rcp_f32_e32 v34, v3
	s_nop 0
	v_mul_f32_e32 v3, v16, v34
	s_nop 0
	v_rcp_f32_e32 v16, v2
	s_nop 0
	v_mul_f32_e32 v2, v5, v16
	v_pk_mul_f32 v[2:3], v[28:29], v[2:3]
	v_lshlrev_b32_e32 v5, 16, v17
	v_and_b32_e32 v17, 0xffff0000, v17
	v_cvt_pk_bf16_f32 v16, v2, v3
	v_mul_f32_e32 v2, 0xbfb8aa3b, v5
	v_mul_f32_e32 v3, 0xbfb8aa3b, v17
	v_exp_f32_e32 v2, v2
	v_exp_f32_e32 v3, v3
	v_pk_mul_f32 v[28:29], v[30:31], v[4:5] op_sel_hi:[1,0]
	v_pk_add_f32 v[2:3], v[2:3], 1.0 op_sel_hi:[1,0]
	s_nop 0
	v_pk_mul_f32 v[28:29], v[28:29], v[36:37]
	v_rcp_f32_e32 v30, v3
	s_nop 0
	v_mul_f32_e32 v3, v17, v30
	s_nop 0
	v_rcp_f32_e32 v17, v2
	s_nop 0
	v_mul_f32_e32 v2, v5, v17
	v_pk_mul_f32 v[2:3], v[28:29], v[2:3]
	v_lshlrev_b32_e32 v5, 16, v18
	v_and_b32_e32 v18, 0xffff0000, v18
	v_cvt_pk_bf16_f32 v17, v2, v3
	v_mul_f32_e32 v2, 0xbfb8aa3b, v5
	v_mul_f32_e32 v3, 0xbfb8aa3b, v18
	v_exp_f32_e32 v2, v2
	v_exp_f32_e32 v3, v3
	v_pk_mul_f32 v[26:27], v[26:27], v[4:5] op_sel_hi:[1,0]
	v_pk_add_f32 v[2:3], v[2:3], 1.0 op_sel_hi:[1,0]
	v_pk_mul_f32 v[20:21], v[26:27], v[20:21]
	s_nop 0
	v_rcp_f32_e32 v26, v3
	s_nop 0
	v_mul_f32_e32 v3, v18, v26
	s_nop 0
	v_rcp_f32_e32 v18, v2
	s_nop 0
	v_mul_f32_e32 v2, v5, v18
	v_pk_mul_f32 v[2:3], v[20:21], v[2:3]
	v_lshlrev_b32_e32 v5, 16, v19
	v_and_b32_e32 v19, 0xffff0000, v19
	v_cvt_pk_bf16_f32 v18, v2, v3
	v_mul_f32_e32 v2, 0xbfb8aa3b, v5
	v_mul_f32_e32 v3, 0xbfb8aa3b, v19
	v_exp_f32_e32 v2, v2
	v_exp_f32_e32 v3, v3
	v_pk_mul_f32 v[20:21], v[32:33], v[4:5] op_sel_hi:[1,0]
	v_pk_add_f32 v[2:3], v[2:3], 1.0 op_sel_hi:[1,0]
	v_pk_mul_f32 v[20:21], v[20:21], v[22:23]
	s_nop 0
	v_rcp_f32_e32 v22, v3
	s_nop 0
	v_mul_f32_e32 v3, v19, v22
	s_nop 0
	v_rcp_f32_e32 v19, v2
	s_nop 0
	v_mul_f32_e32 v2, v5, v19
	v_pk_mul_f32 v[2:3], v[2:3], v[20:21]
	s_nop 0
	v_cvt_pk_bf16_f32 v19, v2, v3
	global_store_dwordx4 v[120:121], v[16:19], off
	global_load_dwordx4 v[16:19], v[80:81], off offset:80
	s_nop 0
	global_load_dwordx4 v[20:23], v177, s[4:5] offset:176
	global_load_dwordx4 v[26:29], v177, s[4:5] offset:160
	s_waitcnt vmcnt(2)
	v_lshlrev_b32_e32 v5, 16, v16
	v_and_b32_e32 v16, 0xffff0000, v16
	v_mul_f32_e32 v2, 0xbfb8aa3b, v5
	v_mul_f32_e32 v3, 0xbfb8aa3b, v16
	v_exp_f32_e32 v2, v2
	v_exp_f32_e32 v3, v3
	v_pk_mul_f32 v[12:13], v[12:13], v[4:5] op_sel_hi:[1,0]
	v_pk_add_f32 v[2:3], v[2:3], 1.0 op_sel_hi:[1,0]
	s_waitcnt vmcnt(0)
	v_pk_mul_f32 v[12:13], v[12:13], v[26:27]
	s_nop 0
	v_rcp_f32_e32 v26, v3
	s_nop 0
	v_mul_f32_e32 v3, v16, v26
	s_nop 0
	v_rcp_f32_e32 v16, v2
	s_nop 0
	v_mul_f32_e32 v2, v5, v16
	v_pk_mul_f32 v[2:3], v[12:13], v[2:3]
	v_lshlrev_b32_e32 v5, 16, v17
	v_and_b32_e32 v13, 0xffff0000, v17
	v_cvt_pk_bf16_f32 v12, v2, v3
	v_mul_f32_e32 v2, 0xbfb8aa3b, v5
	v_mul_f32_e32 v3, 0xbfb8aa3b, v13
	v_exp_f32_e32 v2, v2
	v_exp_f32_e32 v3, v3
	v_pk_mul_f32 v[14:15], v[14:15], v[4:5] op_sel_hi:[1,0]
	v_pk_add_f32 v[2:3], v[2:3], 1.0 op_sel_hi:[1,0]
	s_nop 0
	v_pk_mul_f32 v[14:15], v[14:15], v[28:29]
	v_rcp_f32_e32 v16, v3
	s_nop 0
	v_mul_f32_e32 v3, v13, v16
	s_nop 0
	v_rcp_f32_e32 v13, v2
	s_nop 0
	v_mul_f32_e32 v2, v5, v13
	v_pk_mul_f32 v[2:3], v[14:15], v[2:3]
	v_lshlrev_b32_e32 v5, 16, v18
	v_and_b32_e32 v14, 0xffff0000, v18
	v_cvt_pk_bf16_f32 v13, v2, v3
	v_mul_f32_e32 v2, 0xbfb8aa3b, v5
	v_mul_f32_e32 v3, 0xbfb8aa3b, v14
	v_exp_f32_e32 v2, v2
	v_exp_f32_e32 v3, v3
	v_pk_mul_f32 v[10:11], v[10:11], v[4:5] op_sel_hi:[1,0]
	v_pk_add_f32 v[2:3], v[2:3], 1.0 op_sel_hi:[1,0]
	s_nop 0
	v_pk_mul_f32 v[10:11], v[10:11], v[20:21]
	v_rcp_f32_e32 v15, v3
	s_nop 0
	v_mul_f32_e32 v3, v14, v15
	s_nop 0
	v_rcp_f32_e32 v14, v2
	s_nop 0
	v_mul_f32_e32 v2, v5, v14
	v_pk_mul_f32 v[2:3], v[10:11], v[2:3]
	v_lshlrev_b32_e32 v5, 16, v19
	v_and_b32_e32 v15, 0xffff0000, v19
	v_cvt_pk_bf16_f32 v14, v2, v3
	v_mul_f32_e32 v2, 0xbfb8aa3b, v5
	v_mul_f32_e32 v3, 0xbfb8aa3b, v15
	v_exp_f32_e32 v2, v2
	v_exp_f32_e32 v3, v3
	v_pk_mul_f32 v[10:11], v[24:25], v[4:5] op_sel_hi:[1,0]
	v_pk_add_f32 v[2:3], v[2:3], 1.0 op_sel_hi:[1,0]
	s_nop 0
	v_pk_mul_f32 v[10:11], v[10:11], v[22:23]
	v_rcp_f32_e32 v16, v3
	s_nop 0
	v_mul_f32_e32 v3, v15, v16
	s_nop 0
	v_rcp_f32_e32 v15, v2
	s_nop 0
	v_mul_f32_e32 v2, v5, v15
	v_pk_mul_f32 v[2:3], v[2:3], v[10:11]
	s_nop 0
	v_cvt_pk_bf16_f32 v15, v2, v3
	global_store_dwordx4 v[122:123], v[12:15], off offset:512
	global_load_dwordx4 v[10:13], v[80:81], off offset:96
	s_waitcnt vmcnt(0)
	v_lshlrev_b32_e32 v5, 16, v10
	v_mul_f32_e32 v2, 0xbfb8aa3b, v5
	v_exp_f32_e32 v18, v2
	v_pk_mul_f32 v[20:21], v[0:1], v[4:5] op_sel_hi:[1,0]
	global_load_dwordx4 v[14:17], v177, s[4:5] offset:208
	global_load_dwordx4 v[0:3], v177, s[4:5] offset:192
	v_and_b32_e32 v10, 0xffff0000, v10
	v_mul_f32_e32 v19, 0xbfb8aa3b, v10
	v_exp_f32_e32 v19, v19
	s_waitcnt vmcnt(0)
	v_pk_mul_f32 v[0:1], v[20:21], v[0:1]
	v_pk_add_f32 v[18:19], v[18:19], 1.0 op_sel_hi:[1,0]
	s_nop 0
	s_nop 0
	v_rcp_f32_e32 v20, v19
	s_nop 0
	v_mul_f32_e32 v19, v10, v20
	s_nop 0
	v_rcp_f32_e32 v10, v18
	s_nop 0
	v_mul_f32_e32 v18, v5, v10
	v_pk_mul_f32 v[0:1], v[0:1], v[18:19]
	v_and_b32_e32 v5, 0xffff0000, v11
	v_cvt_pk_bf16_f32 v0, v0, v1
	v_lshlrev_b32_e32 v1, 16, v11
	v_pk_mul_f32 v[8:9], v[8:9], v[4:5] op_sel_hi:[1,0]
	v_mul_f32_e32 v10, 0xbfb8aa3b, v1
	v_pk_mul_f32 v[2:3], v[8:9], v[2:3]
	v_mul_f32_e32 v8, 0xbfb8aa3b, v5
	v_exp_f32_e32 v10, v10
	v_exp_f32_e32 v11, v8
	s_nop 0
	v_pk_add_f32 v[8:9], v[10:11], 1.0 op_sel_hi:[1,0]
	s_nop 0
	s_nop 0
	v_rcp_f32_e32 v10, v9
	s_nop 0
	v_mul_f32_e32 v9, v5, v10
	s_nop 0
	v_rcp_f32_e32 v5, v8
	s_nop 0
	v_mul_f32_e32 v8, v1, v5
	v_pk_mul_f32 v[2:3], v[2:3], v[8:9]
	v_lshlrev_b32_e32 v5, 16, v12
	v_and_b32_e32 v10, 0xffff0000, v12
	v_cvt_pk_bf16_f32 v1, v2, v3
	v_mul_f32_e32 v2, 0xbfb8aa3b, v5
	v_mul_f32_e32 v3, 0xbfb8aa3b, v10
	v_exp_f32_e32 v2, v2
	v_exp_f32_e32 v3, v3
	v_mov_b32_e32 v8, v82
	v_mov_b32_e32 v9, v84
	v_pk_mul_f32 v[8:9], v[8:9], v[4:5] op_sel_hi:[1,0]
	v_pk_add_f32 v[2:3], v[2:3], 1.0 op_sel_hi:[1,0]
	v_pk_mul_f32 v[8:9], v[8:9], v[14:15]
	v_mov_b32_e32 v84, v83
	v_rcp_f32_e32 v11, v3
	s_nop 0
	v_mul_f32_e32 v3, v10, v11
	s_nop 0
	v_rcp_f32_e32 v10, v2
	s_nop 0
	v_mul_f32_e32 v2, v5, v10
	v_pk_mul_f32 v[2:3], v[8:9], v[2:3]
	v_and_b32_e32 v5, 0xffff0000, v13
	v_cvt_pk_bf16_f32 v2, v2, v3
	v_lshlrev_b32_e32 v3, 16, v13
	v_mul_f32_e32 v8, 0xbfb8aa3b, v3
	v_mul_f32_e32 v9, 0xbfb8aa3b, v5
	v_exp_f32_e32 v8, v8
	v_exp_f32_e32 v9, v9
	v_pk_mul_f32 v[10:11], v[84:85], v[4:5] op_sel_hi:[1,0]
	v_pk_add_f32 v[8:9], v[8:9], 1.0 op_sel_hi:[1,0]
	s_nop 0
	v_pk_mul_f32 v[10:11], v[10:11], v[16:17]
	v_rcp_f32_e32 v12, v9
	s_nop 0
	v_mul_f32_e32 v9, v5, v12
	s_nop 0
	v_rcp_f32_e32 v5, v8
	s_nop 0
	v_mul_f32_e32 v8, v3, v5
	v_pk_mul_f32 v[8:9], v[8:9], v[10:11]
	v_add_u32_e32 v5, -8, v70
	v_cvt_pk_bf16_f32 v3, v8, v9
	v_lshrrev_b32_e32 v8, 4, v5
	v_mov_b32_e32 v9, v177
	v_lshlrev_b64 v[8:9], 10, v[8:9]
	v_lshl_add_u64 v[8:9], v[6:7], 0, v[8:9]
	v_lshl_add_u64 v[8:9], v[8:9], 0, v[176:177]
	global_store_dwordx4 v[8:9], v[0:3], off
	global_load_dwordx4 v[0:3], v[80:81], off offset:112
	v_mov_b32_e32 v9, v78
	v_mov_b32_e32 v78, v77
	s_waitcnt vmcnt(0)
	v_lshlrev_b32_e32 v5, 16, v0
	v_mul_f32_e32 v8, 0xbfb8aa3b, v5
	v_exp_f32_e32 v16, v8
	v_mov_b32_e32 v8, v76
	v_pk_mul_f32 v[18:19], v[8:9], v[4:5] op_sel_hi:[1,0]
	global_load_dwordx4 v[8:11], v177, s[4:5] offset:240
	global_load_dwordx4 v[12:15], v177, s[4:5] offset:224
	v_and_b32_e32 v0, 0xffff0000, v0
	v_mul_f32_e32 v17, 0xbfb8aa3b, v0
	v_exp_f32_e32 v17, v17
	s_waitcnt vmcnt(0)
	v_pk_mul_f32 v[12:13], v[18:19], v[12:13]
	v_pk_add_f32 v[16:17], v[16:17], 1.0 op_sel_hi:[1,0]
	s_nop 0
	s_nop 0
	v_rcp_f32_e32 v18, v17
	s_nop 0
	v_mul_f32_e32 v17, v0, v18
	s_nop 0
	v_rcp_f32_e32 v0, v16
	s_nop 0
	v_mul_f32_e32 v16, v5, v0
	v_pk_mul_f32 v[12:13], v[12:13], v[16:17]
	v_lshlrev_b32_e32 v5, 16, v1
	v_and_b32_e32 v1, 0xffff0000, v1
	v_cvt_pk_bf16_f32 v0, v12, v13
	v_mul_f32_e32 v12, 0xbfb8aa3b, v5
	v_mul_f32_e32 v13, 0xbfb8aa3b, v1
	v_exp_f32_e32 v12, v12
	v_exp_f32_e32 v13, v13
	v_pk_mul_f32 v[16:17], v[78:79], v[4:5] op_sel_hi:[1,0]
	v_pk_add_f32 v[12:13], v[12:13], 1.0 op_sel_hi:[1,0]
	v_pk_mul_f32 v[14:15], v[16:17], v[14:15]
	s_nop 0
	v_rcp_f32_e32 v16, v13
	s_nop 0
	v_mul_f32_e32 v13, v1, v16
	s_nop 0
	v_rcp_f32_e32 v1, v12
	s_nop 0
	v_mul_f32_e32 v12, v5, v1
	v_pk_mul_f32 v[12:13], v[14:15], v[12:13]
	v_lshlrev_b32_e32 v5, 16, v2
	v_and_b32_e32 v2, 0xffff0000, v2
	v_cvt_pk_bf16_f32 v1, v12, v13
	v_mul_f32_e32 v12, 0xbfb8aa3b, v5
	v_mul_f32_e32 v13, 0xbfb8aa3b, v2
	v_exp_f32_e32 v12, v12
	v_exp_f32_e32 v13, v13
	v_mov_b32_e32 v14, v72
	v_mov_b32_e32 v15, v74
	v_pk_mul_f32 v[14:15], v[14:15], v[4:5] op_sel_hi:[1,0]
	v_pk_add_f32 v[12:13], v[12:13], 1.0 op_sel_hi:[1,0]
	v_pk_mul_f32 v[8:9], v[14:15], v[8:9]
	v_mov_b32_e32 v74, v73
	v_rcp_f32_e32 v14, v13
	s_nop 0
	v_mul_f32_e32 v13, v2, v14
	s_nop 0
	v_rcp_f32_e32 v2, v12
	s_nop 0
	v_mul_f32_e32 v12, v5, v2
	v_pk_mul_f32 v[8:9], v[8:9], v[12:13]
	v_lshlrev_b32_e32 v12, 16, v3
	v_and_b32_e32 v3, 0xffff0000, v3
	v_cvt_pk_bf16_f32 v2, v8, v9
	v_mul_f32_e32 v5, 0xbfb8aa3b, v12
	v_mul_f32_e32 v9, 0xbfb8aa3b, v3
	v_exp_f32_e32 v8, v5
	v_exp_f32_e32 v9, v9
	v_pk_mul_f32 v[4:5], v[74:75], v[4:5] op_sel_hi:[1,0]
	v_pk_add_f32 v[8:9], v[8:9], 1.0 op_sel_hi:[1,0]
	v_pk_mul_f32 v[4:5], v[4:5], v[10:11]
	s_nop 0
	v_rcp_f32_e32 v10, v9
	s_nop 0
	v_mul_f32_e32 v9, v3, v10
	s_nop 0
	v_rcp_f32_e32 v3, v8
	s_nop 0
	v_mul_f32_e32 v8, v12, v3
	v_pk_mul_f32 v[4:5], v[8:9], v[4:5]
	v_cmp_le_i32_e32 vcc, s2, v69
	v_cvt_pk_bf16_f32 v3, v4, v5
	v_lshrrev_b32_e32 v4, 4, v70
	v_mov_b32_e32 v5, v177
	v_lshlrev_b64 v[4:5], 10, v[4:5]
	v_lshl_add_u64 v[4:5], v[6:7], 0, v[4:5]
	v_lshl_add_u64 v[4:5], v[4:5], 0, v[176:177]
	s_or_b64 s[6:7], vcc, s[6:7]
	global_store_dwordx4 v[4:5], v[0:3], off offset:512
	s_andn2_b64 exec, exec, s[6:7]
	s_cbranch_execnz .LBB0_870

.LBB0_1032:
	s_add_i32 s8, s1, 4
	s_min_u32 s9, s8, 31
	s_lshl_b32 s96, s9, 13
	v_lshl_add_u64 v[168:169], v[186:187], 0, s[96:97]
	v_add_co_u32_e32 v172, vcc, s85, v168
	s_add_i32 s8, s1, 2
	s_nop 0
	v_addc_co_u32_e32 v173, vcc, 0, v169, vcc
	global_load_dwordx4 v[168:171], v[168:169], off
	s_nop 0
	global_load_dwordx4 v[172:175], v[172:173], off
	ds_read_b128 v[196:199], v241
	ds_read_b128 v[200:203], v241 offset:2560
	ds_read_b128 v[204:207], v241 offset:5120
	ds_read_b128 v[242:245], v241 offset:7680
	s_lshl_b32 s96, s9, 11
	s_waitcnt vmcnt(10) lgkmcnt(3)
	v_mfma_f32_32x32x16_bf16 v[112:127], v[160:163], v[196:199], v[112:127]
	s_min_u32 s1, s8, 28
	s_add_i32 s1, s1, 3
	s_waitcnt lgkmcnt(2)
	v_mfma_f32_32x32x16_bf16 v[96:111], v[160:163], v[200:203], v[96:111]
	s_waitcnt vmcnt(7)
	v_mfma_f32_32x32x16_bf16 v[80:95], v[164:167], v[196:199], v[80:95]
	ds_read_b128 v[196:199], v241 offset:5152
	s_waitcnt lgkmcnt(2)
	v_mfma_f32_32x32x16_bf16 v[48:63], v[160:163], v[204:207], v[48:63]
	v_mfma_f32_32x32x16_bf16 v[64:79], v[164:167], v[200:203], v[64:79]
	ds_read_b128 v[200:203], v241 offset:7712
	s_waitcnt lgkmcnt(2)
	v_mfma_f32_32x32x16_bf16 v[32:47], v[160:163], v[242:245], v[32:47]
	ds_read_b128 v[160:163], v241 offset:32
	v_mfma_f32_32x32x16_bf16 v[16:31], v[164:167], v[204:207], v[16:31]
	v_mfma_f32_32x32x16_bf16 v[0:15], v[164:167], v[242:245], v[0:15]
	ds_read_b128 v[164:167], v241 offset:2592
	s_waitcnt vmcnt(3)
	ds_write_b128 v188, v[140:143] offset:10240
	s_waitcnt vmcnt(2)
	ds_write_b128 v188, v[144:147] offset:15360
	v_lshl_add_u64 v[140:141], v[184:185], 0, s[96:97]
	v_add_co_u32_e32 v142, vcc, s41, v140
	s_lshl_b32 s96, s1, 13
	s_nop 0
	v_addc_co_u32_e32 v143, vcc, 0, v141, vcc
	v_lshl_add_u64 v[144:145], v[186:187], 0, s[96:97]
	v_add_co_u32_e32 v146, vcc, s85, v144
	s_waitcnt lgkmcnt(3)
	v_mfma_f32_32x32x16_bf16 v[112:127], v[148:151], v[160:163], v[112:127]
	v_addc_co_u32_e32 v147, vcc, 0, v145, vcc
	s_waitcnt lgkmcnt(2)
	v_mfma_f32_32x32x16_bf16 v[96:111], v[148:151], v[164:167], v[96:111]
	v_mfma_f32_32x32x16_bf16 v[48:63], v[148:151], v[196:199], v[48:63]
	v_mfma_f32_32x32x16_bf16 v[32:47], v[148:151], v[200:203], v[32:47]
	v_mfma_f32_32x32x16_bf16 v[80:95], v[128:131], v[160:163], v[80:95]
	v_mfma_f32_32x32x16_bf16 v[64:79], v[128:131], v[164:167], v[64:79]
	global_load_dwordx4 v[164:167], v[142:143], off
	global_load_dwordx4 v[160:163], v[140:141], off
	global_load_dwordx4 v[148:151], v[140:141], off offset:1024
	v_mfma_f32_32x32x16_bf16 v[16:31], v[128:131], v[196:199], v[16:31]
	v_mfma_f32_32x32x16_bf16 v[0:15], v[128:131], v[200:203], v[0:15]
	global_load_dwordx4 v[128:131], v[142:143], off offset:1024
	s_waitcnt lgkmcnt(0)
	s_barrier
	global_load_dwordx4 v[140:143], v[144:145], off
	s_nop 0
	global_load_dwordx4 v[144:147], v[146:147], off
	ds_read_b128 v[196:199], v241 offset:10240
	ds_read_b128 v[200:203], v241 offset:12800
	ds_read_b128 v[204:207], v241 offset:15360
	ds_read_b128 v[242:245], v241 offset:17920
	s_lshl_b32 s96, s1, 11
	s_waitcnt lgkmcnt(3)
	v_mfma_f32_32x32x16_bf16 v[112:127], v[152:155], v[196:199], v[112:127]
	s_mov_b32 s1, s8
	s_cmp_lt_u32 s8, 30
	s_waitcnt lgkmcnt(2)
	v_mfma_f32_32x32x16_bf16 v[96:111], v[152:155], v[200:203], v[96:111]
	v_mfma_f32_32x32x16_bf16 v[80:95], v[156:159], v[196:199], v[80:95]
	ds_read_b128 v[196:199], v241 offset:15392
	s_waitcnt lgkmcnt(2)
	v_mfma_f32_32x32x16_bf16 v[48:63], v[152:155], v[204:207], v[48:63]
	v_mfma_f32_32x32x16_bf16 v[64:79], v[156:159], v[200:203], v[64:79]
	ds_read_b128 v[200:203], v241 offset:17952
	s_waitcnt lgkmcnt(2)
	v_mfma_f32_32x32x16_bf16 v[32:47], v[152:155], v[242:245], v[32:47]
	ds_read_b128 v[152:155], v241 offset:10272
	v_mfma_f32_32x32x16_bf16 v[16:31], v[156:159], v[204:207], v[16:31]
	v_mfma_f32_32x32x16_bf16 v[0:15], v[156:159], v[242:245], v[0:15]
	ds_read_b128 v[156:159], v241 offset:12832
	s_waitcnt lgkmcnt(1)
	v_mfma_f32_32x32x16_bf16 v[112:127], v[136:139], v[152:155], v[112:127]
	s_waitcnt lgkmcnt(0)
	v_mfma_f32_32x32x16_bf16 v[96:111], v[136:139], v[156:159], v[96:111]
	v_mfma_f32_32x32x16_bf16 v[48:63], v[136:139], v[196:199], v[48:63]
	v_mfma_f32_32x32x16_bf16 v[32:47], v[136:139], v[200:203], v[32:47]
	v_lshl_add_u64 v[136:137], v[184:185], 0, s[96:97]
	v_mfma_f32_32x32x16_bf16 v[16:31], v[132:135], v[196:199], v[16:31]
	v_add_co_u32_e32 v196, vcc, s41, v136
	s_nop 1
	v_addc_co_u32_e32 v197, vcc, 0, v137, vcc
	v_mfma_f32_32x32x16_bf16 v[80:95], v[132:135], v[152:155], v[80:95]
	v_mfma_f32_32x32x16_bf16 v[64:79], v[132:135], v[156:159], v[64:79]
	global_load_dwordx4 v[156:159], v[196:197], off
	global_load_dwordx4 v[152:155], v[136:137], off
	s_nop 0
	global_load_dwordx4 v[136:139], v[136:137], off offset:1024
	v_mfma_f32_32x32x16_bf16 v[0:15], v[132:135], v[200:203], v[0:15]
	global_load_dwordx4 v[132:135], v[196:197], off offset:1024
	s_waitcnt vmcnt(11)
	ds_write_b128 v188, v[168:171]
	s_waitcnt vmcnt(10)
	ds_write_b128 v188, v[172:175] offset:5120
	s_waitcnt lgkmcnt(0)
	s_barrier
	s_cbranch_scc1 .LBB0_1032
	s_waitcnt vmcnt(0)
	v_mul_f32_e32 v133, 0xbfb8aa3b, v112
	v_exp_f32_e32 v133, v133
	s_movk_i32 s1, 0x2400
	v_mul_lo_u32 v128, v238, s1
	v_lshl_or_b32 v131, s0, 6, v181
	v_add_f32_e32 v133, 1.0, v133
	v_lshl_or_b32 v132, v239, 1, v128
	v_and_b32_e32 v129, 0xffffffc0, v237
	v_lshl_or_b32 v128, v181, 1, v128
	v_rcp_f32_e32 v135, v133
	s_nop 0
	v_mul_f32_e32 v112, v112, v135
	v_mul_f32_e32 v96, v96, v112
	v_cvt_pk_bf16_f32 v112, v96, s0
	s_movk_i32 s0, 0x240
	v_mad_u32_u24 v96, v183, s0, v132
	ds_write_b16 v96, v112
	v_mul_f32_e32 v112, 0xbfb8aa3b, v113
	v_exp_f32_e32 v112, v112
	v_lshl_add_u32 v130, s7, 8, v129
	v_lshrrev_b32_e32 v129, 2, v240
	v_mad_u32_u24 v128, v129, s42, v128
	v_add_f32_e32 v112, 1.0, v112
	v_rcp_f32_e32 v133, v112
	s_nop 0
	v_mul_f32_e32 v112, v113, v133
	v_mul_f32_e32 v97, v97, v112
	v_cvt_pk_bf16_f32 v97, v97, s0
	ds_write_b16 v96, v97 offset:144
	v_mul_f32_e32 v97, 0xbfb8aa3b, v114
	v_exp_f32_e32 v97, v97
	s_nop 0
	v_add_f32_e32 v97, 1.0, v97
	v_rcp_f32_e32 v113, v97
	s_nop 0
	v_mul_f32_e32 v97, v114, v113
	v_mul_f32_e32 v97, v98, v97
	v_cvt_pk_bf16_f32 v97, v97, s0
	ds_write_b16 v96, v97 offset:288
	v_mul_f32_e32 v97, 0xbfb8aa3b, v115
	v_exp_f32_e32 v97, v97
	s_nop 0
	v_add_f32_e32 v97, 1.0, v97
	v_rcp_f32_e32 v112, v97
	s_nop 0
	v_mul_f32_e32 v97, v115, v112
	v_mul_f32_e32 v97, v99, v97
	v_cvt_pk_bf16_f32 v97, v97, s0
	ds_write_b16 v96, v97 offset:432
	v_mul_f32_e32 v97, 0xbfb8aa3b, v116
	v_exp_f32_e32 v97, v97
	s_nop 0
	v_add_f32_e32 v97, 1.0, v97
	v_rcp_f32_e32 v99, v97
	s_nop 0
	v_mul_f32_e32 v97, v116, v99
	v_mul_f32_e32 v97, v100, v97
	v_cvt_pk_bf16_f32 v97, v97, s0
	ds_write_b16 v96, v97 offset:1152
	v_mul_f32_e32 v97, 0xbfb8aa3b, v117
	v_exp_f32_e32 v97, v97
	s_nop 0
	v_add_f32_e32 v97, 1.0, v97
	v_rcp_f32_e32 v99, v97
	s_nop 0
	v_mul_f32_e32 v97, v117, v99
	v_mul_f32_e32 v97, v101, v97
	v_cvt_pk_bf16_f32 v97, v97, s0
	ds_write_b16 v96, v97 offset:1296
	v_mul_f32_e32 v97, 0xbfb8aa3b, v118
	v_exp_f32_e32 v97, v97
	s_nop 0
	v_add_f32_e32 v97, 1.0, v97
	v_rcp_f32_e32 v99, v97
	s_nop 0
	v_mul_f32_e32 v97, v118, v99
	v_mul_f32_e32 v97, v102, v97
	v_cvt_pk_bf16_f32 v97, v97, s0
	ds_write_b16 v96, v97 offset:1440
	v_mul_f32_e32 v97, 0xbfb8aa3b, v119
	v_exp_f32_e32 v97, v97
	s_nop 0
	v_add_f32_e32 v97, 1.0, v97
	v_rcp_f32_e32 v99, v97
	s_nop 0
	v_mul_f32_e32 v97, v119, v99
	v_mul_f32_e32 v97, v103, v97
	v_cvt_pk_bf16_f32 v97, v97, s0
	ds_write_b16 v96, v97 offset:1584
	v_mul_f32_e32 v97, 0xbfb8aa3b, v120
	v_exp_f32_e32 v97, v97
	s_nop 0
	v_add_f32_e32 v97, 1.0, v97
	v_rcp_f32_e32 v99, v97
	s_nop 0
	v_mul_f32_e32 v97, v120, v99
	v_mul_f32_e32 v97, v104, v97
	v_cvt_pk_bf16_f32 v97, v97, s0
	ds_write_b16 v96, v97 offset:2304
	v_mul_f32_e32 v97, 0xbfb8aa3b, v121
	v_exp_f32_e32 v97, v97
	s_nop 0
	v_add_f32_e32 v97, 1.0, v97
	v_rcp_f32_e32 v99, v97
	s_nop 0
	v_mul_f32_e32 v97, v121, v99
	v_mul_f32_e32 v97, v105, v97
	v_cvt_pk_bf16_f32 v97, v97, s0
	ds_write_b16 v96, v97 offset:2448
	v_mul_f32_e32 v97, 0xbfb8aa3b, v122
	v_exp_f32_e32 v97, v97
	s_nop 0
	v_add_f32_e32 v97, 1.0, v97
	v_rcp_f32_e32 v99, v97
	s_nop 0
	v_mul_f32_e32 v97, v122, v99
	v_mul_f32_e32 v97, v106, v97
	v_cvt_pk_bf16_f32 v97, v97, s0
	ds_write_b16 v96, v97 offset:2592
	v_mul_f32_e32 v97, 0xbfb8aa3b, v123
	v_exp_f32_e32 v97, v97
	s_nop 0
	v_add_f32_e32 v97, 1.0, v97
	v_rcp_f32_e32 v99, v97
	s_nop 0
	v_mul_f32_e32 v97, v123, v99
	v_mul_f32_e32 v97, v107, v97
	v_cvt_pk_bf16_f32 v97, v97, s0
	ds_write_b16 v96, v97 offset:2736
	v_mul_f32_e32 v97, 0xbfb8aa3b, v124
	v_exp_f32_e32 v97, v97
	s_nop 0
	v_add_f32_e32 v97, 1.0, v97
	v_rcp_f32_e32 v99, v97
	s_nop 0
	v_mul_f32_e32 v97, v124, v99
	v_mul_f32_e32 v97, v108, v97
	v_cvt_pk_bf16_f32 v97, v97, s0
	ds_write_b16 v96, v97 offset:3456
	v_mul_f32_e32 v97, 0xbfb8aa3b, v125
	v_exp_f32_e32 v97, v97
	s_nop 0
	v_add_f32_e32 v97, 1.0, v97
	v_rcp_f32_e32 v99, v97
	s_nop 0
	v_mul_f32_e32 v97, v125, v99
	v_mul_f32_e32 v97, v109, v97
	v_cvt_pk_bf16_f32 v97, v97, s0
	ds_write_b16 v96, v97 offset:3600
	v_mul_f32_e32 v97, 0xbfb8aa3b, v126
	v_exp_f32_e32 v97, v97
	s_nop 0
	v_add_f32_e32 v97, 1.0, v97
	v_rcp_f32_e32 v99, v97
	s_nop 0
	v_mul_f32_e32 v97, v126, v99
	v_mul_f32_e32 v97, v110, v97
	v_cvt_pk_bf16_f32 v97, v97, s0
	ds_write_b16 v96, v97 offset:3744
	v_mul_f32_e32 v97, 0xbfb8aa3b, v127
	v_exp_f32_e32 v97, v97
	s_nop 0
	v_add_f32_e32 v97, 1.0, v97
	v_rcp_f32_e32 v99, v97
	s_nop 0
	v_mul_f32_e32 v97, v127, v99
	v_mul_f32_e32 v97, v111, v97
	v_cvt_pk_bf16_f32 v97, v97, s0
	ds_write_b16 v96, v97 offset:3888
	v_mul_f32_e32 v97, 0xbfb8aa3b, v80
	v_exp_f32_e32 v97, v97
	s_nop 0
	v_add_f32_e32 v97, 1.0, v97
	v_rcp_f32_e32 v99, v97
	s_nop 0
	v_mul_f32_e32 v80, v80, v99
	v_mul_f32_e32 v64, v64, v80
	v_cvt_pk_bf16_f32 v64, v64, s0
	ds_write_b16 v96, v64 offset:4608
	v_mul_f32_e32 v64, 0xbfb8aa3b, v81
	v_exp_f32_e32 v64, v64
	s_nop 0
	v_add_f32_e32 v64, 1.0, v64
	v_rcp_f32_e32 v97, v64
	s_nop 0
	v_mul_f32_e32 v64, v81, v97
	v_mul_f32_e32 v64, v65, v64
	v_cvt_pk_bf16_f32 v64, v64, s0
	ds_write_b16 v96, v64 offset:4752
	v_mul_f32_e32 v64, 0xbfb8aa3b, v82
	v_exp_f32_e32 v64, v64
	s_nop 0
	v_add_f32_e32 v64, 1.0, v64
	v_rcp_f32_e32 v80, v64
	s_nop 0
	v_mul_f32_e32 v64, v82, v80
	v_mul_f32_e32 v64, v66, v64
	v_cvt_pk_bf16_f32 v64, v64, s0
	ds_write_b16 v96, v64 offset:4896
	v_mul_f32_e32 v64, 0xbfb8aa3b, v83
	v_exp_f32_e32 v64, v64
	s_nop 0
	v_add_f32_e32 v64, 1.0, v64
	v_rcp_f32_e32 v66, v64
	s_nop 0
	v_mul_f32_e32 v64, v83, v66
	v_mul_f32_e32 v64, v67, v64
	v_cvt_pk_bf16_f32 v64, v64, s0
	ds_write_b16 v96, v64 offset:5040
	v_mul_f32_e32 v64, 0xbfb8aa3b, v84
	v_exp_f32_e32 v64, v64
	s_nop 0
	v_add_f32_e32 v64, 1.0, v64
	v_rcp_f32_e32 v66, v64
	s_nop 0
	v_mul_f32_e32 v64, v84, v66
	v_mul_f32_e32 v64, v68, v64
	v_cvt_pk_bf16_f32 v64, v64, s0
	ds_write_b16 v96, v64 offset:5760
	v_mul_f32_e32 v64, 0xbfb8aa3b, v85
	v_exp_f32_e32 v64, v64
	s_nop 0
	v_add_f32_e32 v64, 1.0, v64
	v_rcp_f32_e32 v66, v64
	s_nop 0
	v_mul_f32_e32 v64, v85, v66
	v_mul_f32_e32 v64, v69, v64
	v_cvt_pk_bf16_f32 v64, v64, s0
	ds_write_b16 v96, v64 offset:5904
	v_mul_f32_e32 v64, 0xbfb8aa3b, v86
	v_exp_f32_e32 v64, v64
	s_nop 0
	v_add_f32_e32 v64, 1.0, v64
	v_rcp_f32_e32 v66, v64
	s_nop 0
	v_mul_f32_e32 v64, v86, v66
	v_mul_f32_e32 v64, v70, v64
	v_cvt_pk_bf16_f32 v64, v64, s0
	ds_write_b16 v96, v64 offset:6048
	v_mul_f32_e32 v64, 0xbfb8aa3b, v87
	v_exp_f32_e32 v64, v64
	s_nop 0
	v_add_f32_e32 v64, 1.0, v64
	v_rcp_f32_e32 v66, v64
	s_nop 0
	v_mul_f32_e32 v64, v87, v66
	v_mul_f32_e32 v64, v71, v64
	v_cvt_pk_bf16_f32 v64, v64, s0
	ds_write_b16 v96, v64 offset:6192
	v_mul_f32_e32 v64, 0xbfb8aa3b, v88
	v_exp_f32_e32 v64, v64
	v_ashrrev_i32_e32 v71, 5, v130
	v_or_b32_e32 v70, 1, v71
	v_add_f32_e32 v64, 1.0, v64
	v_rcp_f32_e32 v66, v64
	s_nop 0
	v_mul_f32_e32 v64, v88, v66
	v_mul_f32_e32 v64, v72, v64
	v_cvt_pk_bf16_f32 v64, v64, s0
	ds_write_b16 v96, v64 offset:6912
	v_mul_f32_e32 v64, 0xbfb8aa3b, v89
	v_exp_f32_e32 v64, v64
	s_nop 0
	v_add_f32_e32 v64, 1.0, v64
	v_rcp_f32_e32 v66, v64
	s_nop 0
	v_mul_f32_e32 v64, v89, v66
	v_mul_f32_e32 v64, v73, v64
	v_cvt_pk_bf16_f32 v64, v64, s0
	ds_write_b16 v96, v64 offset:7056
	v_mul_f32_e32 v64, 0xbfb8aa3b, v90
	v_exp_f32_e32 v64, v64
	s_nop 0
	v_add_f32_e32 v64, 1.0, v64
	v_rcp_f32_e32 v66, v64
	s_nop 0
	v_mul_f32_e32 v64, v90, v66
	v_mul_f32_e32 v64, v74, v64
	v_cvt_pk_bf16_f32 v64, v64, s0
	ds_write_b16 v96, v64 offset:7200
	v_mul_f32_e32 v64, 0xbfb8aa3b, v91
	v_exp_f32_e32 v64, v64
	s_nop 0
	v_add_f32_e32 v64, 1.0, v64
	v_rcp_f32_e32 v66, v64
	s_nop 0
	v_mul_f32_e32 v64, v91, v66
	v_mul_f32_e32 v64, v75, v64
	v_cvt_pk_bf16_f32 v64, v64, s0
	ds_write_b16 v96, v64 offset:7344
	v_mul_f32_e32 v64, 0xbfb8aa3b, v92
	v_exp_f32_e32 v64, v64
	s_nop 0
	v_add_f32_e32 v64, 1.0, v64
	v_rcp_f32_e32 v66, v64
	s_nop 0
	v_mul_f32_e32 v64, v92, v66
	v_mul_f32_e32 v64, v76, v64
	v_cvt_pk_bf16_f32 v64, v64, s0
	ds_write_b16 v96, v64 offset:8064
	v_mul_f32_e32 v64, 0xbfb8aa3b, v93
	v_exp_f32_e32 v64, v64
	s_nop 0
	v_add_f32_e32 v64, 1.0, v64
	v_rcp_f32_e32 v66, v64
	s_nop 0
	v_mul_f32_e32 v64, v93, v66
	v_mul_f32_e32 v64, v77, v64
	v_cvt_pk_bf16_f32 v64, v64, s0
	ds_write_b16 v96, v64 offset:8208
	v_mul_f32_e32 v64, 0xbfb8aa3b, v94
	v_exp_f32_e32 v64, v64
	s_nop 0
	v_add_f32_e32 v64, 1.0, v64
	v_rcp_f32_e32 v66, v64
	s_nop 0
	v_mul_f32_e32 v64, v94, v66
	v_mul_f32_e32 v64, v78, v64
	v_cvt_pk_bf16_f32 v64, v64, s0
	ds_write_b16 v96, v64 offset:8352
	v_mul_f32_e32 v64, 0xbfb8aa3b, v95
	v_exp_f32_e32 v64, v64
	s_nop 0
	v_add_f32_e32 v64, 1.0, v64
	v_rcp_f32_e32 v66, v64
	s_nop 0
	v_mul_f32_e32 v64, v95, v66
	v_mul_f32_e32 v64, v79, v64
	v_cvt_pk_bf16_f32 v64, v64, s0
	ds_write_b16 v96, v64 offset:8496
	v_ashrrev_i32_e32 v68, 4, v131
	s_waitcnt lgkmcnt(0)
	v_ashrrev_i32_e32 v69, 31, v68
	ds_read_b128 v[72:75], v128
	v_mad_i64_i32 v[64:65], s[0:1], v71, s23, v[68:69]
	v_lshlrev_b64 v[64:65], 10, v[64:65]
	v_lshlrev_b32_e32 v66, 6, v181
	v_lshl_add_u64 v[64:65], s[66:67], 0, v[64:65]
	v_and_b32_e32 v176, 0x200, v66
	v_lshl_add_u64 v[76:77], v[64:65], 0, v[176:177]
	v_lshlrev_b32_e32 v66, 4, v129
	v_mov_b32_e32 v67, v177
	v_lshl_add_u64 v[64:65], v[76:77], 0, v[66:67]
	s_waitcnt lgkmcnt(0)
	global_store_dwordx4 v[64:65], v[72:75], off
	ds_read_b128 v[72:75], v128 offset:2304
	v_or_b32_e32 v64, 0x100, v66
	v_mov_b32_e32 v65, v177
	v_lshl_add_u64 v[76:77], v[76:77], 0, v[64:65]
	s_waitcnt lgkmcnt(0)
	global_store_dwordx4 v[76:77], v[72:75], off
	ds_read_b128 v[72:75], v128 offset:4608
	v_mad_i64_i32 v[76:77], s[0:1], v70, s23, v[68:69]
	v_lshlrev_b64 v[76:77], 10, v[76:77]
	v_lshl_add_u64 v[76:77], s[66:67], 0, v[76:77]
	v_lshl_add_u64 v[76:77], v[76:77], 0, v[176:177]
	v_lshl_add_u64 v[78:79], v[76:77], 0, v[66:67]
	v_mul_f32_e32 v69, 0xbfb8aa3b, v48
	s_waitcnt lgkmcnt(0)
	global_store_dwordx4 v[78:79], v[72:75], off
	ds_read_b128 v[72:75], v128 offset:6912
	v_exp_f32_e32 v69, v69
	v_lshl_add_u64 v[76:77], v[76:77], 0, v[64:65]
	v_add_f32_e32 v69, 1.0, v69
	s_waitcnt lgkmcnt(0)
	global_store_dwordx4 v[76:77], v[72:75], off
	s_waitcnt lgkmcnt(0)
	s_nop 1
	v_rcp_f32_e32 v73, v69
	s_nop 0
	v_mul_f32_e32 v48, v48, v73
	v_mul_f32_e32 v32, v32, v48
	v_cvt_pk_bf16_f32 v32, v32, s0
	ds_write_b16 v96, v32
	v_mul_f32_e32 v32, 0xbfb8aa3b, v49
	v_exp_f32_e32 v32, v32
	s_nop 0
	v_add_f32_e32 v32, 1.0, v32
	v_rcp_f32_e32 v69, v32
	s_nop 0
	v_mul_f32_e32 v32, v49, v69
	v_mul_f32_e32 v32, v33, v32
	v_cvt_pk_bf16_f32 v32, v32, s0
	ds_write_b16 v96, v32 offset:144
	v_mul_f32_e32 v32, 0xbfb8aa3b, v50
	v_exp_f32_e32 v32, v32
	s_nop 0
	v_add_f32_e32 v32, 1.0, v32
	v_rcp_f32_e32 v48, v32
	s_nop 0
	v_mul_f32_e32 v32, v50, v48
	v_mul_f32_e32 v32, v34, v32
	v_cvt_pk_bf16_f32 v32, v32, s0
	ds_write_b16 v96, v32 offset:288
	v_mul_f32_e32 v32, 0xbfb8aa3b, v51
	v_exp_f32_e32 v32, v32
	s_nop 0
	v_add_f32_e32 v32, 1.0, v32
	v_rcp_f32_e32 v34, v32
	s_nop 0
	v_mul_f32_e32 v32, v51, v34
	v_mul_f32_e32 v32, v35, v32
	v_cvt_pk_bf16_f32 v32, v32, s0
	ds_write_b16 v96, v32 offset:432
	v_mul_f32_e32 v32, 0xbfb8aa3b, v52
	v_exp_f32_e32 v32, v32
	s_nop 0
	v_add_f32_e32 v32, 1.0, v32
	v_rcp_f32_e32 v34, v32
	s_nop 0
	v_mul_f32_e32 v32, v52, v34
	v_mul_f32_e32 v32, v36, v32
	v_cvt_pk_bf16_f32 v32, v32, s0
	ds_write_b16 v96, v32 offset:1152
	v_mul_f32_e32 v32, 0xbfb8aa3b, v53
	v_exp_f32_e32 v32, v32
	s_nop 0
	v_add_f32_e32 v32, 1.0, v32
	v_rcp_f32_e32 v34, v32
	s_nop 0
	v_mul_f32_e32 v32, v53, v34
	v_mul_f32_e32 v32, v37, v32
	v_cvt_pk_bf16_f32 v32, v32, s0
	ds_write_b16 v96, v32 offset:1296
	v_mul_f32_e32 v32, 0xbfb8aa3b, v54
	v_exp_f32_e32 v32, v32
	s_nop 0
	v_add_f32_e32 v32, 1.0, v32
	v_rcp_f32_e32 v34, v32
	s_nop 0
	v_mul_f32_e32 v32, v54, v34
	v_mul_f32_e32 v32, v38, v32
	v_cvt_pk_bf16_f32 v32, v32, s0
	ds_write_b16 v96, v32 offset:1440
	v_mul_f32_e32 v32, 0xbfb8aa3b, v55
	v_exp_f32_e32 v32, v32
	s_nop 0
	v_add_f32_e32 v32, 1.0, v32
	v_rcp_f32_e32 v34, v32
	s_nop 0
	v_mul_f32_e32 v32, v55, v34
	v_mul_f32_e32 v32, v39, v32
	v_cvt_pk_bf16_f32 v32, v32, s0
	ds_write_b16 v96, v32 offset:1584
	v_mul_f32_e32 v32, 0xbfb8aa3b, v56
	v_exp_f32_e32 v32, v32
	s_nop 0
	v_add_f32_e32 v32, 1.0, v32
	v_rcp_f32_e32 v34, v32
	s_nop 0
	v_mul_f32_e32 v32, v56, v34
	v_mul_f32_e32 v32, v40, v32
	v_cvt_pk_bf16_f32 v32, v32, s0
	ds_write_b16 v96, v32 offset:2304
	v_mul_f32_e32 v32, 0xbfb8aa3b, v57
	v_exp_f32_e32 v32, v32
	s_nop 0
	v_add_f32_e32 v32, 1.0, v32
	v_rcp_f32_e32 v34, v32
	s_nop 0
	v_mul_f32_e32 v32, v57, v34
	v_mul_f32_e32 v32, v41, v32
	v_cvt_pk_bf16_f32 v32, v32, s0
	ds_write_b16 v96, v32 offset:2448
	v_mul_f32_e32 v32, 0xbfb8aa3b, v58
	v_exp_f32_e32 v32, v32
	s_nop 0
	v_add_f32_e32 v32, 1.0, v32
	v_rcp_f32_e32 v34, v32
	s_nop 0
	v_mul_f32_e32 v32, v58, v34
	v_mul_f32_e32 v32, v42, v32
	v_cvt_pk_bf16_f32 v32, v32, s0
	ds_write_b16 v96, v32 offset:2592
	v_mul_f32_e32 v32, 0xbfb8aa3b, v59
	v_exp_f32_e32 v32, v32
	s_nop 0
	v_add_f32_e32 v32, 1.0, v32
	v_rcp_f32_e32 v34, v32
	s_nop 0
	v_mul_f32_e32 v32, v59, v34
	v_mul_f32_e32 v32, v43, v32
	v_cvt_pk_bf16_f32 v32, v32, s0
	ds_write_b16 v96, v32 offset:2736
	v_mul_f32_e32 v32, 0xbfb8aa3b, v60
	v_exp_f32_e32 v32, v32
	s_nop 0
	v_add_f32_e32 v32, 1.0, v32
	v_rcp_f32_e32 v34, v32
	s_nop 0
	v_mul_f32_e32 v32, v60, v34
	v_mul_f32_e32 v32, v44, v32
	v_cvt_pk_bf16_f32 v32, v32, s0
	ds_write_b16 v96, v32 offset:3456
	v_mul_f32_e32 v32, 0xbfb8aa3b, v61
	v_exp_f32_e32 v32, v32
	s_nop 0
	v_add_f32_e32 v32, 1.0, v32
	v_rcp_f32_e32 v34, v32
	s_nop 0
	v_mul_f32_e32 v32, v61, v34
	v_mul_f32_e32 v32, v45, v32
	v_cvt_pk_bf16_f32 v32, v32, s0
	ds_write_b16 v96, v32 offset:3600
	v_mul_f32_e32 v32, 0xbfb8aa3b, v62
	v_exp_f32_e32 v32, v32
	s_nop 0
	v_add_f32_e32 v32, 1.0, v32
	v_rcp_f32_e32 v34, v32
	s_nop 0
	v_mul_f32_e32 v32, v62, v34
	v_mul_f32_e32 v32, v46, v32
	v_cvt_pk_bf16_f32 v32, v32, s0
	ds_write_b16 v96, v32 offset:3744
	v_mul_f32_e32 v32, 0xbfb8aa3b, v63
	v_exp_f32_e32 v32, v32
	s_nop 0
	v_add_f32_e32 v32, 1.0, v32
	v_rcp_f32_e32 v34, v32
	s_nop 0
	v_mul_f32_e32 v32, v63, v34
	v_mul_f32_e32 v32, v47, v32
	v_cvt_pk_bf16_f32 v32, v32, s0
	ds_write_b16 v96, v32 offset:3888
	v_mul_f32_e32 v32, 0xbfb8aa3b, v16
	v_exp_f32_e32 v32, v32
	s_nop 0
	v_add_f32_e32 v32, 1.0, v32
	v_rcp_f32_e32 v34, v32
	s_nop 0
	v_mul_f32_e32 v16, v16, v34
	v_mul_f32_e32 v0, v0, v16
	v_cvt_pk_bf16_f32 v0, v0, s0
	ds_write_b16 v96, v0 offset:4608
	v_mul_f32_e32 v0, 0xbfb8aa3b, v17
	v_exp_f32_e32 v0, v0
	s_nop 0
	v_add_f32_e32 v0, 1.0, v0
	v_rcp_f32_e32 v32, v0
	s_nop 0
	v_mul_f32_e32 v0, v17, v32
	v_mul_f32_e32 v0, v1, v0
	v_cvt_pk_bf16_f32 v0, v0, s0
	ds_write_b16 v96, v0 offset:4752
	v_mul_f32_e32 v0, 0xbfb8aa3b, v18
	v_exp_f32_e32 v0, v0
	s_nop 0
	v_add_f32_e32 v0, 1.0, v0
	v_rcp_f32_e32 v16, v0
	s_nop 0
	v_mul_f32_e32 v0, v18, v16
	v_mul_f32_e32 v0, v2, v0
	v_cvt_pk_bf16_f32 v0, v0, s0
	ds_write_b16 v96, v0 offset:4896
	v_mul_f32_e32 v0, 0xbfb8aa3b, v19
	v_exp_f32_e32 v0, v0
	s_nop 0
	v_add_f32_e32 v0, 1.0, v0
	v_rcp_f32_e32 v2, v0
	s_nop 0
	v_mul_f32_e32 v0, v19, v2
	v_mul_f32_e32 v0, v3, v0
	v_cvt_pk_bf16_f32 v0, v0, s0
	ds_write_b16 v96, v0 offset:5040
	v_mul_f32_e32 v0, 0xbfb8aa3b, v20
	v_exp_f32_e32 v0, v0
	s_nop 0
	v_add_f32_e32 v0, 1.0, v0
	v_rcp_f32_e32 v2, v0
	s_nop 0
	v_mul_f32_e32 v0, v20, v2
	v_mul_f32_e32 v0, v4, v0
	v_cvt_pk_bf16_f32 v0, v0, s0
	ds_write_b16 v96, v0 offset:5760
	v_mul_f32_e32 v0, 0xbfb8aa3b, v21
	v_exp_f32_e32 v0, v0
	s_nop 0
	v_add_f32_e32 v0, 1.0, v0
	v_rcp_f32_e32 v2, v0
	s_nop 0
	v_mul_f32_e32 v0, v21, v2
	v_mul_f32_e32 v0, v5, v0
	v_cvt_pk_bf16_f32 v0, v0, s0
	ds_write_b16 v96, v0 offset:5904
	v_mul_f32_e32 v0, 0xbfb8aa3b, v22
	v_exp_f32_e32 v0, v0
	s_nop 0
	v_add_f32_e32 v0, 1.0, v0
	v_rcp_f32_e32 v2, v0
	s_nop 0
	v_mul_f32_e32 v0, v22, v2
	v_mul_f32_e32 v0, v6, v0
	v_cvt_pk_bf16_f32 v0, v0, s0
	ds_write_b16 v96, v0 offset:6048
	v_mul_f32_e32 v0, 0xbfb8aa3b, v23
	v_exp_f32_e32 v0, v0
	s_nop 0
	v_add_f32_e32 v0, 1.0, v0
	v_rcp_f32_e32 v2, v0
	s_nop 0
	v_mul_f32_e32 v0, v23, v2
	v_mul_f32_e32 v0, v7, v0
	v_cvt_pk_bf16_f32 v0, v0, s0
	ds_write_b16 v96, v0 offset:6192
	v_mul_f32_e32 v0, 0xbfb8aa3b, v24
	v_exp_f32_e32 v0, v0
	s_nop 0
	v_add_f32_e32 v0, 1.0, v0
	v_rcp_f32_e32 v2, v0
	s_nop 0
	v_mul_f32_e32 v0, v24, v2
	v_mul_f32_e32 v0, v8, v0
	v_cvt_pk_bf16_f32 v0, v0, s0
	ds_write_b16 v96, v0 offset:6912
	v_mul_f32_e32 v0, 0xbfb8aa3b, v25
	v_exp_f32_e32 v0, v0
	s_nop 0
	v_add_f32_e32 v0, 1.0, v0
	v_rcp_f32_e32 v2, v0
	s_nop 0
	v_mul_f32_e32 v0, v25, v2
	v_mul_f32_e32 v0, v9, v0
	v_cvt_pk_bf16_f32 v0, v0, s0
	ds_write_b16 v96, v0 offset:7056
	v_mul_f32_e32 v0, 0xbfb8aa3b, v26
	v_exp_f32_e32 v0, v0
	s_nop 0
	v_add_f32_e32 v0, 1.0, v0
	v_rcp_f32_e32 v2, v0
	s_nop 0
	v_mul_f32_e32 v0, v26, v2
	v_mul_f32_e32 v0, v10, v0
	v_cvt_pk_bf16_f32 v0, v0, s0
	ds_write_b16 v96, v0 offset:7200
	v_mul_f32_e32 v0, 0xbfb8aa3b, v27
	v_exp_f32_e32 v0, v0
	s_nop 0
	v_add_f32_e32 v0, 1.0, v0
	v_rcp_f32_e32 v2, v0
	s_nop 0
	v_mul_f32_e32 v0, v27, v2
	v_mul_f32_e32 v0, v11, v0
	v_cvt_pk_bf16_f32 v0, v0, s0
	ds_write_b16 v96, v0 offset:7344
	v_mul_f32_e32 v0, 0xbfb8aa3b, v28
	v_exp_f32_e32 v0, v0
	s_nop 0
	v_add_f32_e32 v0, 1.0, v0
	v_rcp_f32_e32 v2, v0
	s_nop 0
	v_mul_f32_e32 v0, v28, v2
	v_mul_f32_e32 v0, v12, v0
	v_cvt_pk_bf16_f32 v0, v0, s0
	ds_write_b16 v96, v0 offset:8064
	v_mul_f32_e32 v0, 0xbfb8aa3b, v29
	v_exp_f32_e32 v0, v0
	s_nop 0
	v_add_f32_e32 v0, 1.0, v0
	v_rcp_f32_e32 v2, v0
	s_nop 0
	v_mul_f32_e32 v0, v29, v2
	v_mul_f32_e32 v0, v13, v0
	v_cvt_pk_bf16_f32 v0, v0, s0
	ds_write_b16 v96, v0 offset:8208
	v_mul_f32_e32 v0, 0xbfb8aa3b, v30
	v_exp_f32_e32 v0, v0
	s_nop 0
	v_add_f32_e32 v0, 1.0, v0
	v_rcp_f32_e32 v2, v0
	s_nop 0
	v_mul_f32_e32 v0, v30, v2
	v_mul_f32_e32 v0, v14, v0
	v_cvt_pk_bf16_f32 v0, v0, s0
	ds_write_b16 v96, v0 offset:8352
	v_mul_f32_e32 v0, 0xbfb8aa3b, v31
	v_exp_f32_e32 v0, v0
	s_nop 0
	v_add_f32_e32 v0, 1.0, v0
	v_rcp_f32_e32 v2, v0
	s_nop 0
	v_mul_f32_e32 v0, v31, v2
	v_mul_f32_e32 v0, v15, v0
	v_cvt_pk_bf16_f32 v0, v0, s0
	ds_write_b16 v96, v0 offset:8496
	v_or_b32_e32 v4, 2, v68
	s_waitcnt lgkmcnt(0)
	v_ashrrev_i32_e32 v5, 31, v4
	ds_read_b128 v[0:3], v128
	v_mad_i64_i32 v[6:7], s[0:1], v71, s23, v[4:5]
	v_lshlrev_b64 v[6:7], 10, v[6:7]
	v_lshl_add_u64 v[6:7], s[66:67], 0, v[6:7]
	v_lshl_add_u64 v[6:7], v[6:7], 0, v[176:177]
	v_lshl_add_u64 v[8:9], v[6:7], 0, v[66:67]
	s_waitcnt lgkmcnt(0)
	global_store_dwordx4 v[8:9], v[0:3], off
	ds_read_b128 v[0:3], v128 offset:2304
	v_lshl_add_u64 v[6:7], v[6:7], 0, v[64:65]
	v_mad_i64_i32 v[4:5], s[0:1], v70, s23, v[4:5]
	v_lshlrev_b64 v[4:5], 10, v[4:5]
	s_waitcnt lgkmcnt(0)
	global_store_dwordx4 v[6:7], v[0:3], off
	ds_read_b128 v[0:3], v128 offset:4608
	v_lshl_add_u64 v[4:5], s[66:67], 0, v[4:5]
	v_lshl_add_u64 v[4:5], v[4:5], 0, v[176:177]
	v_lshl_add_u64 v[6:7], v[4:5], 0, v[66:67]
	v_lshl_add_u64 v[4:5], v[4:5], 0, v[64:65]
	s_waitcnt lgkmcnt(0)
	global_store_dwordx4 v[6:7], v[0:3], off
	ds_read_b128 v[0:3], v128 offset:6912
	v_readlane_b32 s0, v254, 11
	s_add_i32 s2, s2, s0
	s_cmp_lt_i32 s2, s3
	s_waitcnt lgkmcnt(0)
	global_store_dwordx4 v[4:5], v[0:3], off
	s_waitcnt lgkmcnt(0)
	s_barrier
	s_cbranch_scc1 .LBB0_1031
